# attention tiles: drop fminf canonicalising v_max (128x), split v_pk_add/mul_f32 into scalar pairs (104x); bit-identical math
# speedup vs baseline: 1.0054x; 1.0054x over previous
; #define LAS __attribute__((address_space(3)))
; #define ATT_SB() do {} while (0)
; #define ATT_SB() do {} while (0)
; #define ATT_SB() __builtin_amdgcn_sched_barrier(0)
; #define ATT_VLD(f) do { const int c_ = (f) >> 2, s_ = (f) & 3; const s16x4 lo_ = vtr(vbp + 4096 * s_ + vbase[0] + vcq[c_]); const s16x4 hh_ = vtr(vbp + 4096 * s_ + vbase[1] + vcq[c_]); \
;         vf[f] = (bf16x8){lo_[0], lo_[1], lo_[2], lo_[3], hh_[0], hh_[1], hh_[2], hh_[3]}; } while (0)
; #define ATT_PV(f) do { if (DO_PV) { o[(f) >> 2] = __builtin_amdgcn_mfma_f32_32x32x16_bf16(pa[(f) & 3], vf[f], o[(f) >> 2], 0, 0, 0); if ((f) + 4 < 16) ATT_VLD((f) + 4); } } while (0)
; #define ATT_EXP8(i) do { _Pragma("unroll") for (int r_ = 0; r_ < 8; ++r_) p[(i) >> 1][8 * ((i) & 1) + r_] = __builtin_amdgcn_exp2f(fminf(p[(i) >> 1][8 * ((i) & 1) + r_], 30.f)); } while (0)
; template <bool DO_PV> ...
;     f32x16 p[2];
; #pragma unroll
;     for (int r = 0; r < 16; ++r) { p[0][r] = 0.f; p[1][r] = 0.f; }
;     bf16x8 vf[16];
;     if (DO_PV) { ATT_VLD(0); ATT_VLD(1); ATT_VLD(2); ATT_VLD(3); }
;     {
;         bf16x8 ka[8], kc[8];
; #pragma unroll
;         for (int d0 = 0; d0 < 8; ++d0) { ka[d0] = *(const LAS bf16x8*)(kb + koff[d0]); kc[d0] = *(const LAS bf16x8*)(kb + 8192 + koff[d0]); }
;         ATT_SB();
; #pragma unroll
;         for (int d0 = 0; d0 < 8; ++d0) {
;             p[0] = __builtin_amdgcn_mfma_f32_32x32x16_bf16(ka[d0], qf[d0], p[0], 0, 0, 0);
;             p[1] = __builtin_amdgcn_mfma_f32_32x32x16_bf16(kc[d0], qf[d0], p[1], 0, 0, 0);
;         }
;     }
;     ATT_SB();
;     const bool need_mask = (k0 + 63 >= qw0);
;     float L[8], T[8];
;     ATT_PV(0); ATT_EXP8(0); ATT_SB();
;     ATT_PV(1); ATT_EXP8(1); ATT_SB();
;     ATT_PV(2); ATT_EXP8(2); ATT_SB();
;     ATT_PV(3); ATT_EXP8(3); ATT_SB();
.LBB0_598:
	s_cmp_lt_i32 s65, s66
	s_cselect_b64 s[52:53], -1, 0
	s_cmp_ge_i32 s65, s66
	s_cbranch_scc1 .LBB0_608
	s_xor_b64 s[6:7], s[4:5], -1
	s_add_i32 s8, s8, 0
	s_mov_b64 s[4:5], -1
	s_and_b64 vcc, exec, s[6:7]
	v_add_u32_e32 v168, s8, v179
	v_add_u32_e32 v167, s8, v180
	v_add_u32_e32 v166, s8, v181
	v_add_u32_e32 v165, s8, v182
	v_add_u32_e32 v164, s8, v183
	v_add_u32_e32 v163, s8, v184
	v_add_u32_e32 v162, s8, v185
	v_add_u32_e32 v149, s8, v186
	s_cbranch_vccz .LBB0_603
	ds_read_b128 v[64:67], v168
	ds_read_b128 v[68:71], v168 offset:8192
	ds_read_b128 v[170:173], v167
	ds_read_b128 v[174:177], v167 offset:8192
	s_add_i32 s4, s65, 63
	s_cmp_lt_i32 s4, s64
	s_waitcnt lgkmcnt(0)
	v_mfma_f32_32x32x16_bf16 v[80:95], v[64:67], v[96:99], 0
	v_mfma_f32_32x32x16_bf16 v[80:95], v[170:173], v[100:103], v[80:95]
	ds_read_b128 v[170:173], v166
	ds_read_b128 v[196:199], v166 offset:8192
	v_mfma_f32_32x32x16_bf16 v[64:79], v[68:71], v[96:99], 0
	s_waitcnt lgkmcnt(0)
	v_mfma_f32_32x32x16_bf16 v[80:95], v[170:173], v[104:107], v[80:95]
	ds_read_b128 v[170:173], v165
	ds_read_b128 v[200:203], v165 offset:8192
	v_mfma_f32_32x32x16_bf16 v[64:79], v[174:177], v[100:103], v[64:79]
	s_waitcnt lgkmcnt(0)
	v_mfma_f32_32x32x16_bf16 v[80:95], v[170:173], v[108:111], v[80:95]
	ds_read_b128 v[170:173], v164
	ds_read_b128 v[204:207], v164 offset:8192
	v_mfma_f32_32x32x16_bf16 v[64:79], v[196:199], v[104:107], v[64:79]
	s_waitcnt lgkmcnt(0)
	v_mfma_f32_32x32x16_bf16 v[80:95], v[170:173], v[112:115], v[80:95]
	ds_read_b128 v[170:173], v163
	ds_read_b128 v[208:211], v163 offset:8192
	v_mfma_f32_32x32x16_bf16 v[64:79], v[200:203], v[108:111], v[64:79]
	s_waitcnt lgkmcnt(0)
	v_mfma_f32_32x32x16_bf16 v[80:95], v[170:173], v[116:119], v[80:95]
	ds_read_b128 v[170:173], v162
	ds_read_b128 v[212:215], v162 offset:8192
	v_mfma_f32_32x32x16_bf16 v[64:79], v[204:207], v[112:115], v[64:79]
	s_waitcnt lgkmcnt(0)
	v_mfma_f32_32x32x16_bf16 v[80:95], v[170:173], v[120:123], v[80:95]
	ds_read_b128 v[170:173], v149
	ds_read_b128 v[216:219], v149 offset:8192
	v_mfma_f32_32x32x16_bf16 v[64:79], v[208:211], v[116:119], v[64:79]
	s_waitcnt lgkmcnt(0)
	v_mfma_f32_32x32x16_bf16 v[80:95], v[170:173], v[124:127], v[80:95]
	v_mfma_f32_32x32x16_bf16 v[64:79], v[212:215], v[120:123], v[64:79]
	s_nop 10
	v_min_f32_e32 v81, 0x41f00000, v81
	v_exp_f32_e32 v160, v81
	v_min_f32_e32 v81, 0x41f00000, v82
	v_exp_f32_e32 v161, v81
	v_min_f32_e32 v81, 0x41f00000, v83
	v_mfma_f32_32x32x16_bf16 v[64:79], v[216:219], v[124:127], v[64:79]
	v_min_f32_e32 v83, 0x41f00000, v85
	v_min_f32_e32 v82, 0x41f00000, v84
	v_exp_f32_e32 v84, v83
	v_min_f32_e32 v83, 0x41f00000, v86
	v_exp_f32_e32 v85, v83
	v_min_f32_e32 v83, 0x41f00000, v87
	v_min_f32_e32 v87, 0x41f00000, v89
	v_min_f32_e32 v86, 0x41f00000, v88
	v_exp_f32_e32 v88, v87
	v_min_f32_e32 v87, 0x41f00000, v90
	v_exp_f32_e32 v89, v87
	v_min_f32_e32 v87, 0x41f00000, v91
	v_min_f32_e32 v91, 0x41f00000, v93
	v_min_f32_e32 v65, 0x41f00000, v65
	v_min_f32_e32 v90, 0x41f00000, v92
	v_exp_f32_e32 v92, v91
	v_min_f32_e32 v91, 0x41f00000, v94
	v_exp_f32_e32 v94, v65
	v_min_f32_e32 v65, 0x41f00000, v66
	v_exp_f32_e32 v93, v91
	v_min_f32_e32 v91, 0x41f00000, v95
	v_exp_f32_e32 v95, v65
	v_min_f32_e32 v65, 0x41f00000, v67
	v_min_f32_e32 v67, 0x41f00000, v69
	v_min_f32_e32 v66, 0x41f00000, v68
	v_exp_f32_e32 v68, v67
	v_min_f32_e32 v67, 0x41f00000, v70
	v_exp_f32_e32 v69, v67
	v_min_f32_e32 v67, 0x41f00000, v71
	v_min_f32_e32 v71, 0x41f00000, v73
	v_min_f32_e32 v70, 0x41f00000, v72
	v_exp_f32_e32 v72, v71
	v_min_f32_e32 v71, 0x41f00000, v74
	v_exp_f32_e32 v73, v71
	v_min_f32_e32 v71, 0x41f00000, v75
	v_min_f32_e32 v75, 0x41f00000, v77
	v_min_f32_e32 v74, 0x41f00000, v76
	v_exp_f32_e32 v76, v75
	v_min_f32_e32 v75, 0x41f00000, v78
	v_exp_f32_e32 v77, v75
	v_min_f32_e32 v80, 0x41f00000, v80
	v_min_f32_e32 v64, 0x41f00000, v64
	v_min_f32_e32 v75, 0x41f00000, v79
	v_exp_f32_e32 v80, v80
	v_exp_f32_e32 v81, v81
	v_exp_f32_e32 v82, v82
	v_exp_f32_e32 v83, v83
	v_exp_f32_e32 v86, v86
	v_exp_f32_e32 v87, v87
	v_exp_f32_e32 v90, v90
	v_exp_f32_e32 v91, v91
	v_exp_f32_e32 v64, v64
	v_exp_f32_e32 v65, v65
	v_exp_f32_e32 v66, v66
	v_exp_f32_e32 v67, v67
	v_exp_f32_e32 v70, v70
	v_exp_f32_e32 v71, v71
	v_exp_f32_e32 v74, v74
	v_exp_f32_e32 v75, v75
	s_cbranch_scc1 .LBB0_602
; __device__ __forceinline__ int crow(int r, int hi) { return (r & 3) + 8 * (r >> 2) + 4 * hi; }
; #define ATT_SB() do {} while (0)
; #define ATT_SB() do {} while (0)
; #define ATT_SB() __builtin_amdgcn_sched_barrier(0)
; #define ATT_PV(f) do { if (DO_PV) { o[(f) >> 2] = __builtin_amdgcn_mfma_f32_32x32x16_bf16(pa[(f) & 3], vf[f], o[(f) >> 2], 0, 0, 0); if ((f) + 4 < 16) ATT_VLD((f) + 4); } } while (0)
; #define ATT_LBLK(j) do { const int ph_ = 1 - ((j) >> 2), g_ = 3 - ((j) & 3); \
;         const float w0_ = 1.0f + p[ph_][4 * g_], w1_ = 1.0f + p[ph_][4 * g_ + 1], w2_ = 1.0f + p[ph_][4 * g_ + 2], w3_ = 1.0f + p[ph_][4 * g_ + 3]; \
;         L[j] = __builtin_amdgcn_logf((w0_ * w1_) * (w2_ * w3_)); } while (0)
; template <bool DO_PV> ...
;     ...
;     if (need_mask) {
; #pragma unroll
;         for (int ph = 0; ph < 2; ++ph)
; #pragma unroll
;             for (int r = 0; r < 16; ++r) { const int key = k0 + 32 * ph + crow(r, hi); if (key >= qabs) p[ph][r] = 0.f; }
;     }
;     ATT_SB();
;     ATT_PV(4); ATT_LBLK(0); ATT_LBLK(1); ATT_SB();
;     ATT_PV(5); ATT_LBLK(2); ATT_LBLK(3); ATT_SB();
;     ATT_PV(6); ATT_LBLK(4); ATT_LBLK(5); ATT_SB();
;     ATT_PV(7); ATT_LBLK(6); ATT_LBLK(7); ATT_SB();
	v_add_u32_e32 v78, s65, v187
	v_add_u32_e32 v79, 1, v78
	v_cmp_lt_i32_e32 vcc, v78, v144
	v_cmp_lt_i32_e64 s[4:5], v79, v144
	s_or_b64 vcc, s[4:5], vcc
	v_add_u32_e32 v79, 2, v78
	v_cndmask_b32_e32 v80, 0, v80, vcc
	v_cmp_lt_i32_e32 vcc, v79, v144
	v_add_u32_e32 v79, 3, v78
	v_cndmask_b32_e64 v160, 0, v160, s[4:5]
	v_cndmask_b32_e32 v161, 0, v161, vcc
	v_cmp_lt_i32_e32 vcc, v79, v144
	v_add_u32_e32 v79, 8, v78
	s_nop 0
	v_cndmask_b32_e32 v81, 0, v81, vcc
	v_cmp_lt_i32_e32 vcc, v79, v144
	v_add_u32_e32 v79, 9, v78
	s_nop 0
	v_cndmask_b32_e32 v82, 0, v82, vcc
	v_cmp_lt_i32_e32 vcc, v79, v144
	v_add_u32_e32 v79, 10, v78
	s_nop 0
	v_cndmask_b32_e32 v84, 0, v84, vcc
	v_cmp_lt_i32_e32 vcc, v79, v144
	v_add_u32_e32 v79, 11, v78
	s_nop 0
	v_cndmask_b32_e32 v85, 0, v85, vcc
	v_cmp_lt_i32_e32 vcc, v79, v144
	v_add_u32_e32 v79, 16, v78
	s_nop 0
	v_cndmask_b32_e32 v83, 0, v83, vcc
	v_cmp_lt_i32_e32 vcc, v79, v144
	v_add_u32_e32 v79, 17, v78
	s_nop 0
	v_cndmask_b32_e32 v86, 0, v86, vcc
	v_cmp_lt_i32_e32 vcc, v79, v144
	v_add_u32_e32 v79, 18, v78
	s_nop 0
	v_cndmask_b32_e32 v88, 0, v88, vcc
	v_cmp_lt_i32_e32 vcc, v79, v144
	v_add_u32_e32 v79, 19, v78
	s_nop 0
	v_cndmask_b32_e32 v89, 0, v89, vcc
	v_cmp_lt_i32_e32 vcc, v79, v144
	v_add_u32_e32 v79, 24, v78
	s_nop 0
	v_cndmask_b32_e32 v87, 0, v87, vcc
	v_cmp_lt_i32_e32 vcc, v79, v144
	v_add_u32_e32 v79, 25, v78
	s_nop 0
	v_cndmask_b32_e32 v90, 0, v90, vcc
	v_cmp_lt_i32_e32 vcc, v79, v144
	v_add_u32_e32 v79, 26, v78
	s_nop 0
	v_cndmask_b32_e32 v92, 0, v92, vcc
	v_cmp_lt_i32_e32 vcc, v79, v144
	v_add_u32_e32 v79, 27, v78
	s_nop 0
	v_cndmask_b32_e32 v93, 0, v93, vcc
	v_cmp_lt_i32_e32 vcc, v79, v144
	v_add_u32_e32 v79, 32, v78
	v_cmp_lt_i32_e64 s[4:5], v79, v144
	v_add_u32_e32 v79, 33, v78
	v_cmp_lt_i32_e64 s[6:7], v79, v144
	v_add_u32_e32 v79, 34, v78
	v_cmp_lt_i32_e64 s[8:9], v79, v144
	v_add_u32_e32 v79, 35, v78
	v_cmp_lt_i32_e64 s[10:11], v79, v144
	v_add_u32_e32 v79, 40, v78
	v_cmp_lt_i32_e64 s[12:13], v79, v144
	v_add_u32_e32 v79, 41, v78
	v_cmp_lt_i32_e64 s[14:15], v79, v144
	v_add_u32_e32 v79, 42, v78
	v_cmp_lt_i32_e64 s[16:17], v79, v144
	v_add_u32_e32 v79, 43, v78
	v_cmp_lt_i32_e64 s[18:19], v79, v144
	v_add_u32_e32 v79, 48, v78
	v_cmp_lt_i32_e64 s[20:21], v79, v144
	v_add_u32_e32 v79, 49, v78
	v_cmp_lt_i32_e64 s[22:23], v79, v144
	v_add_u32_e32 v79, 50, v78
	v_cmp_lt_i32_e64 s[24:25], v79, v144
	v_add_u32_e32 v79, 51, v78
	v_cmp_lt_i32_e64 s[26:27], v79, v144
	v_add_u32_e32 v79, 56, v78
	v_cmp_lt_i32_e64 s[28:29], v79, v144
	v_add_u32_e32 v79, 57, v78
	v_cmp_lt_i32_e64 s[30:31], v79, v144
	v_add_u32_e32 v79, 58, v78
	v_add_u32_e32 v78, 59, v78
	v_cmp_lt_i32_e64 s[34:35], v79, v144
	v_cmp_lt_i32_e64 s[36:37], v78, v144
	s_or_b64 s[34:35], s[36:37], s[34:35]
	s_or_b64 s[30:31], s[34:35], s[30:31]
	s_or_b64 s[28:29], s[30:31], s[28:29]
	s_or_b64 s[26:27], s[28:29], s[26:27]
	s_or_b64 s[24:25], s[26:27], s[24:25]
	s_or_b64 s[22:23], s[24:25], s[22:23]
	s_or_b64 s[20:21], s[22:23], s[20:21]
	s_or_b64 s[18:19], s[20:21], s[18:19]
	s_or_b64 s[16:17], s[18:19], s[16:17]
	s_or_b64 s[14:15], s[16:17], s[14:15]
	s_or_b64 s[12:13], s[14:15], s[12:13]
	s_or_b64 s[10:11], s[12:13], s[10:11]
	s_or_b64 s[8:9], s[10:11], s[8:9]
	s_or_b64 s[6:7], s[8:9], s[6:7]
	s_or_b64 s[4:5], s[6:7], s[4:5]
	s_or_b64 vcc, s[4:5], vcc
	v_cndmask_b32_e64 v75, 0, v75, s[36:37]
	v_cndmask_b32_e64 v77, 0, v77, s[34:35]
	v_cndmask_b32_e64 v76, 0, v76, s[30:31]
	v_cndmask_b32_e64 v74, 0, v74, s[28:29]
	v_cndmask_b32_e64 v71, 0, v71, s[26:27]
	v_cndmask_b32_e64 v73, 0, v73, s[24:25]
	v_cndmask_b32_e64 v72, 0, v72, s[22:23]
	v_cndmask_b32_e64 v70, 0, v70, s[20:21]
	v_cndmask_b32_e64 v67, 0, v67, s[18:19]
	v_cndmask_b32_e64 v69, 0, v69, s[16:17]
	v_cndmask_b32_e64 v68, 0, v68, s[14:15]
	v_cndmask_b32_e64 v66, 0, v66, s[12:13]
	v_cndmask_b32_e64 v65, 0, v65, s[10:11]
	v_cndmask_b32_e64 v95, 0, v95, s[8:9]
	v_cndmask_b32_e64 v94, 0, v94, s[6:7]
	v_cndmask_b32_e64 v64, 0, v64, s[4:5]
	v_cndmask_b32_e32 v91, 0, v91, vcc
.LBB0_602:
	v_add_f32_e32 v78, 1.0, v76
	v_add_f32_e32 v79, 1.0, v77
	v_add_f32_e32 v170, 1.0, v74
	v_add_f32_e32 v171, 1.0, v75
	v_add_f32_e32 v174, 1.0, v70
	v_add_f32_e32 v175, 1.0, v71
	v_mul_f32_e32 v172, v78, v170
	v_mul_f32_e32 v173, v79, v171
	v_add_f32_e32 v196, 1.0, v66
	v_add_f32_e32 v197, 1.0, v67
	v_mul_f32_e32 v159, v172, v173
	v_add_f32_e32 v172, 1.0, v72
	v_add_f32_e32 v173, 1.0, v73
	v_add_f32_e32 v200, 1.0, v64
	v_add_f32_e32 v201, 1.0, v65
	v_mul_f32_e32 v176, v172, v174
	v_mul_f32_e32 v177, v173, v175
	v_add_f32_e32 v204, 1.0, v90
	v_add_f32_e32 v205, 1.0, v91
	v_mul_f32_e32 v169, v176, v177
	v_add_f32_e32 v176, 1.0, v68
	v_add_f32_e32 v177, 1.0, v69
	v_log_f32_e32 v159, v159
	v_mul_f32_e32 v198, v176, v196
	v_mul_f32_e32 v199, v177, v197
	v_add_f32_e32 v208, 1.0, v86
	v_add_f32_e32 v209, 1.0, v87
	v_mul_f32_e32 v171, v198, v199
	v_add_f32_e32 v198, 1.0, v94
	v_add_f32_e32 v199, 1.0, v95
	v_add_f32_e32 v212, 1.0, v82
	v_add_f32_e32 v213, 1.0, v83
	v_mul_f32_e32 v202, v198, v200
	v_mul_f32_e32 v203, v199, v201
	v_log_f32_e32 v169, v169
	v_mul_f32_e32 v175, v202, v203
	v_add_f32_e32 v202, 1.0, v92
	v_add_f32_e32 v203, 1.0, v93
	v_add_f32_e32 v216, 1.0, v80
	v_add_f32_e32 v217, 1.0, v81
	v_mul_f32_e32 v206, v202, v204
	v_mul_f32_e32 v207, v203, v205
	v_log_f32_e32 v171, v171
	v_mul_f32_e32 v194, v206, v207
	v_add_f32_e32 v206, 1.0, v88
	v_add_f32_e32 v207, 1.0, v89
	v_log_f32_e32 v175, v175
	v_mul_f32_e32 v210, v206, v208
	v_mul_f32_e32 v211, v207, v209
	v_mov_b32_e32 v209, v159
	v_mul_f32_e32 v197, v210, v211
	v_add_f32_e32 v210, 1.0, v84
	v_add_f32_e32 v211, 1.0, v85
	v_mov_b32_e32 v221, v175
; __device__ __forceinline__ unsigned pk_bf16(float lo, float hi) { return pg8::cvt_pk_bf16(lo, hi); }
; template <bool DO_PV> ...
;     ...
;     for (int s = 0; s < 4; ++s) { const int ph = s >> 1, rb = 8 * (s & 1);
;         u32x4 w; w.x = pk_bf16(p[ph][rb], p[ph][rb + 1]); w.y = pk_bf16(p[ph][rb + 2], p[ph][rb + 3]); w.z = pk_bf16(p[ph][rb + 4], p[ph][rb + 5]); w.w = pk_bf16(p[ph][rb + 6], p[ph][rb + 7]);
;         pa[s] = __builtin_bit_cast(bf16x8, w); }
	v_mul_f32_e32 v214, v210, v212
	v_mul_f32_e32 v215, v211, v213
	v_mov_b32_e32 v213, v159
	s_nop 1
	v_permlane32_swap_b32_e32 v209, v213
	v_mul_f32_e32 v201, v214, v215
	v_add_f32_e32 v214, 1.0, v160
	v_add_f32_e32 v215, 1.0, v161
	v_cmp_eq_f32_e32 vcc, v159, v209
	v_mul_f32_e32 v218, v214, v216
	v_mul_f32_e32 v219, v215, v217
	v_log_f32_e32 v194, v194
	v_cndmask_b32_e32 v217, v209, v213, vcc
	v_cndmask_b32_e64 v217, 0, v217, s[0:1]
	v_add_f32_e32 v217, v158, v217
	v_mul_f32_e32 v205, v218, v219
	v_add_f32_e32 v217, v159, v217
	v_mov_b32_e32 v159, v169
	v_mov_b32_e32 v219, v169
	s_nop 1
	v_permlane32_swap_b32_e32 v159, v219
	v_add_f32_e32 v218, v209, v213
	v_cmp_eq_f32_e32 vcc, v169, v159
	v_mov_b32_e32 v213, v171
	v_log_f32_e32 v197, v197
	v_cndmask_b32_e32 v209, v159, v219, vcc
	v_add_f32_e32 v218, v158, v218
	v_add_f32_e32 v219, v159, v219
	v_mov_b32_e32 v159, v171
	v_cndmask_b32_e64 v209, 0, v209, s[0:1]
	s_nop 0
	v_permlane32_swap_b32_e32 v159, v213
	v_add_f32_e32 v209, v218, v209
	v_add_f32_e32 v218, v218, v219
	v_mov_b32_e32 v219, v218
	v_cmp_eq_f32_e32 vcc, v171, v159
	v_add_f32_e32 v220, v159, v213
	v_log_f32_e32 v201, v201
	v_cndmask_b32_e32 v219, v159, v213, vcc
	v_cndmask_b32_e64 v219, 0, v219, s[0:1]
	v_add_f32_e32 v222, v218, v219
	v_mov_b32_e32 v219, v175
	s_nop 1
	v_permlane32_swap_b32_e32 v219, v221
	v_cmp_eq_f32_e32 vcc, v175, v219
	v_log_f32_e32 v205, v205
	v_exp_f32_e64 v217, -v217
	v_cndmask_b32_e32 v159, v219, v221, vcc
	v_cndmask_b32_e64 v159, 0, v159, s[0:1]
	v_add_f32_e32 v218, v218, v220
	v_add_f32_e32 v219, v219, v221
	v_mov_b32_e32 v221, v197
	v_add_f32_e32 v213, v218, v159
	v_add_f32_e32 v218, v218, v219
	v_mov_b32_e32 v219, v218
	v_mov_b32_e32 v159, v194
	v_mov_b32_e32 v219, v194
	s_nop 1
	v_permlane32_swap_b32_e32 v159, v219
	v_cmp_eq_f32_e32 vcc, v194, v159
	s_mov_b64 s[4:5], 0
	s_nop 0
	v_cndmask_b32_e32 v220, v159, v219, vcc
	v_cndmask_b32_e64 v220, 0, v220, s[0:1]
	v_add_f32_e32 v223, v218, v220
	v_add_f32_e32 v220, v159, v219
	v_mov_b32_e32 v219, v197
	s_nop 1
	v_permlane32_swap_b32_e32 v219, v221
	v_cmp_eq_f32_e32 vcc, v197, v219
	s_nop 1
	v_cndmask_b32_e32 v159, v219, v221, vcc
	v_cndmask_b32_e64 v159, 0, v159, s[0:1]
	v_add_f32_e32 v218, v218, v220
	v_add_f32_e32 v219, v219, v221
	v_mov_b32_e32 v221, v205
	v_add_f32_e32 v224, v218, v159
	v_add_f32_e32 v218, v218, v219
	v_mov_b32_e32 v219, v218
	v_mov_b32_e32 v159, v201
	v_mov_b32_e32 v219, v201
	s_nop 1
	v_permlane32_swap_b32_e32 v159, v219
	v_cmp_eq_f32_e32 vcc, v201, v159
	s_nop 1
	v_cndmask_b32_e32 v220, v159, v219, vcc
	v_cndmask_b32_e64 v220, 0, v220, s[0:1]
	v_add_f32_e32 v225, v218, v220
	v_add_f32_e32 v220, v159, v219
	v_mov_b32_e32 v219, v205
	s_nop 1
	v_permlane32_swap_b32_e32 v219, v221
	v_cmp_eq_f32_e32 vcc, v205, v219
	s_nop 1
	v_cndmask_b32_e32 v159, v219, v221, vcc
	v_cndmask_b32_e64 v159, 0, v159, s[0:1]
	v_add_f32_e32 v218, v218, v220
	v_add_f32_e32 v219, v219, v221
	s_nop 0
	v_add_f32_e32 v220, v218, v159
	v_add_f32_e32 v159, v218, v219
	v_mul_f32_e32 v218, v74, v217
	v_mul_f32_e32 v74, v170, v217
	v_mul_f32_e32 v170, v76, v74
	v_mul_f32_e32 v74, v78, v74
	v_mul_f32_e32 v217, v77, v74
	v_mul_f32_e32 v74, v79, v74
	v_mul_f32_e32 v79, v75, v74
	v_add_f32_e32 v74, v169, v209
	v_exp_f32_e64 v74, -v74
	v_add_f32_e32 v75, v171, v222
	v_add_f32_e32 v76, v194, v223
	v_add_f32_e32 v77, v201, v225
	v_mul_f32_e32 v78, v70, v74
	v_mul_f32_e32 v70, v174, v74
	v_mul_f32_e32 v169, v72, v70
	v_exp_f32_e64 v72, -v75
	v_mul_f32_e32 v70, v172, v70
	v_mul_f32_e32 v171, v73, v70
	v_mul_f32_e32 v70, v173, v70
	v_mul_f32_e32 v74, v66, v72
	v_mul_f32_e32 v66, v196, v72
	v_mul_f32_e32 v75, v68, v66
	v_add_f32_e32 v68, v175, v213
	v_exp_f32_e64 v68, -v68
	v_mul_f32_e32 v66, v176, v66
	v_mul_f32_e32 v173, v69, v66
	v_mul_f32_e32 v66, v177, v66
	v_mul_f32_e32 v174, v67, v66
	v_mul_f32_e32 v72, v64, v68
	v_mul_f32_e32 v64, v200, v68
	v_exp_f32_e64 v66, -v76
	v_mul_f32_e32 v73, v94, v64
	v_mul_f32_e32 v64, v198, v64
	v_mul_f32_e32 v172, v71, v70
	v_add_f32_e32 v70, v197, v224
	v_mul_f32_e32 v76, v95, v64
	v_mul_f32_e32 v64, v199, v64
	v_mul_f32_e32 v94, v65, v64
	v_exp_f32_e64 v65, -v70
	v_mul_f32_e32 v64, v204, v66
	v_mul_f32_e32 v71, v90, v66
	v_mul_f32_e32 v90, v92, v64
	v_mul_f32_e32 v64, v202, v64
	v_mul_f32_e32 v92, v93, v64
	v_mul_f32_e32 v64, v203, v64
	v_mul_f32_e32 v91, v91, v64
	v_mul_f32_e32 v68, v86, v65
	v_mul_f32_e32 v64, v208, v65
	v_exp_f32_e64 v65, -v77
	v_mul_f32_e32 v69, v88, v64
	v_mul_f32_e32 v64, v206, v64
	v_mul_f32_e32 v70, v89, v64
	v_mul_f32_e32 v64, v207, v64
	v_mul_f32_e32 v77, v87, v64
	v_mul_f32_e32 v66, v82, v65
	v_mul_f32_e32 v64, v212, v65
	v_add_f32_e32 v65, v205, v220
	v_exp_f32_e64 v65, -v65
	v_mul_f32_e32 v67, v84, v64
	v_mul_f32_e32 v64, v210, v64
	v_mul_f32_e32 v82, v85, v64
	v_mul_f32_e32 v64, v211, v64
	v_mul_f32_e32 v83, v83, v64
	v_mul_f32_e32 v64, v80, v65
	v_mul_f32_e32 v65, v216, v65
	v_mul_f32_e32 v80, v160, v65
	v_mul_f32_e32 v65, v214, v65
	v_mul_f32_e32 v84, v161, v65
	v_mul_f32_e32 v65, v215, v65
	v_mul_f32_e32 v65, v81, v65
	v_cvt_pk_bf16_f32 v64, v64, v80
	v_cvt_pk_bf16_f32 v65, v84, v65
	v_cvt_pk_bf16_f32 v66, v66, v67
	v_cvt_pk_bf16_f32 v67, v82, v83
	v_cvt_pk_bf16_f32 v68, v68, v69
	v_cvt_pk_bf16_f32 v69, v70, v77
	v_cvt_pk_bf16_f32 v70, v71, v90
	v_cvt_pk_bf16_f32 v71, v92, v91
	v_cvt_pk_bf16_f32 v72, v72, v73
	v_cvt_pk_bf16_f32 v73, v76, v94
	v_cvt_pk_bf16_f32 v74, v74, v75
	v_cvt_pk_bf16_f32 v75, v173, v174
	v_cvt_pk_bf16_f32 v76, v78, v169
	v_cvt_pk_bf16_f32 v77, v171, v172
	v_cvt_pk_bf16_f32 v78, v218, v170
	v_cvt_pk_bf16_f32 v79, v217, v79
; #define LAS __attribute__((address_space(3)))
; #define ATT_SB() do {} while (0)
; #define ATT_SB() do {} while (0)
; #define ATT_SB() __builtin_amdgcn_sched_barrier(0)
; #define ATT_VLD(f) do { const int c_ = (f) >> 2, s_ = (f) & 3; const s16x4 lo_ = vtr(vbp + 4096 * s_ + vbase[0] + vcq[c_]); const s16x4 hh_ = vtr(vbp + 4096 * s_ + vbase[1] + vcq[c_]); \
;         vf[f] = (bf16x8){lo_[0], lo_[1], lo_[2], lo_[3], hh_[0], hh_[1], hh_[2], hh_[3]}; } while (0)
; #define ATT_PV(f) do { if (DO_PV) { o[(f) >> 2] = __builtin_amdgcn_mfma_f32_32x32x16_bf16(pa[(f) & 3], vf[f], o[(f) >> 2], 0, 0, 0); if ((f) + 4 < 16) ATT_VLD((f) + 4); } } while (0)
; #define ATT_EXP8(i) do { _Pragma("unroll") for (int r_ = 0; r_ < 8; ++r_) p[(i) >> 1][8 * ((i) & 1) + r_] = __builtin_amdgcn_exp2f(fminf(p[(i) >> 1][8 * ((i) & 1) + r_], 30.f)); } while (0)
; template <bool DO_PV> ...
;     f32x16 p[2];
; #pragma unroll
;     for (int r = 0; r < 16; ++r) { p[0][r] = 0.f; p[1][r] = 0.f; }
;     bf16x8 vf[16];
;     if (DO_PV) { ATT_VLD(0); ATT_VLD(1); ATT_VLD(2); ATT_VLD(3); }
;     {
;         bf16x8 ka[8], kc[8];
; #pragma unroll
;         for (int d0 = 0; d0 < 8; ++d0) { ka[d0] = *(const LAS bf16x8*)(kb + koff[d0]); kc[d0] = *(const LAS bf16x8*)(kb + 8192 + koff[d0]); }
;         ATT_SB();
; #pragma unroll
;         for (int d0 = 0; d0 < 8; ++d0) {
;             p[0] = __builtin_amdgcn_mfma_f32_32x32x16_bf16(ka[d0], qf[d0], p[0], 0, 0, 0);
;             p[1] = __builtin_amdgcn_mfma_f32_32x32x16_bf16(kc[d0], qf[d0], p[1], 0, 0, 0);
;         }
;     }
;     ATT_SB();
;     const bool need_mask = (k0 + 63 >= qw0);
;     float L[8], T[8];
;     ATT_PV(0); ATT_EXP8(0); ATT_SB();
;     ATT_PV(1); ATT_EXP8(1); ATT_SB();
;     ATT_PV(2); ATT_EXP8(2); ATT_SB();
;     ATT_PV(3); ATT_EXP8(3); ATT_SB();
.LBB0_603:
	s_and_b64 vcc, exec, s[4:5]
	s_cbranch_vccz .LBB0_607
	ds_read_b128 v[64:67], v168
	ds_read_b128 v[68:71], v168 offset:8192
	ds_read_b128 v[168:171], v167
	ds_read_b128 v[172:175], v167 offset:8192
	s_lshl_b32 s4, s73, 14
	s_add_i32 s4, s4, 0
	s_waitcnt lgkmcnt(0)
	v_mfma_f32_32x32x16_bf16 v[80:95], v[64:67], v[96:99], 0
	v_add_u32_e32 v194, s4, v188
	v_add_u32_e32 v159, s4, v189
	v_add_u32_e32 v176, v159, v191
	s_add_i32 s4, s65, 63
	s_cmp_lt_i32 s4, s64
	v_mfma_f32_32x32x16_bf16 v[80:95], v[168:171], v[100:103], v[80:95]
	ds_read_b128 v[168:171], v166
	ds_read_b128 v[196:199], v166 offset:8192
	s_waitcnt lgkmcnt(0)
	v_mfma_f32_32x32x16_bf16 v[80:95], v[168:171], v[104:107], v[80:95]
	ds_read_b128 v[166:169], v165
	ds_read_b128 v[200:203], v165 offset:8192
	v_mfma_f32_32x32x16_bf16 v[64:79], v[68:71], v[96:99], 0
	s_waitcnt lgkmcnt(0)
	v_mfma_f32_32x32x16_bf16 v[80:95], v[166:169], v[108:111], v[80:95]
	ds_read_b128 v[166:169], v164
	ds_read_b128 v[204:207], v164 offset:8192
	ds_read_b128 v[208:211], v163
	v_mfma_f32_32x32x16_bf16 v[64:79], v[172:175], v[100:103], v[64:79]
	s_waitcnt lgkmcnt(0)
	v_mfma_f32_32x32x16_bf16 v[80:95], v[166:169], v[112:115], v[80:95]
	ds_read_b128 v[212:215], v163 offset:8192
	ds_read_b128 v[164:167], v162
	v_add_u32_e32 v168, v194, v190
	v_add_u32_e32 v169, v159, v190
	v_mfma_f32_32x32x16_bf16 v[64:79], v[196:199], v[104:107], v[64:79]
	v_mfma_f32_32x32x16_bf16 v[80:95], v[208:211], v[116:119], v[80:95]
	ds_read_b128 v[208:211], v162 offset:8192
	ds_read_b128 v[160:163], v149
	ds_read_b128 v[216:219], v149 offset:8192
	ds_read_b64_tr_b16 v[220:221], v168 offset:32768
	ds_read_b64_tr_b16 v[224:225], v168 offset:36864
	ds_read_b64_tr_b16 v[228:229], v168 offset:40960
	ds_read_b64_tr_b16 v[232:233], v168 offset:45056
	ds_read_b64_tr_b16 v[222:223], v169 offset:34816
	ds_read_b64_tr_b16 v[226:227], v169 offset:38912
	ds_read_b64_tr_b16 v[230:231], v169 offset:43008
	ds_read_b64_tr_b16 v[234:235], v169 offset:47104
	v_add_u32_e32 v149, v194, v191
	v_mfma_f32_32x32x16_bf16 v[64:79], v[200:203], v[108:111], v[64:79]
	s_waitcnt lgkmcnt(0)
	v_mfma_f32_32x32x16_bf16 v[80:95], v[164:167], v[120:123], v[80:95]
	v_mfma_f32_32x32x16_bf16 v[64:79], v[204:207], v[112:115], v[64:79]
	v_mfma_f32_32x32x16_bf16 v[80:95], v[160:163], v[124:127], v[80:95]
	v_mfma_f32_32x32x16_bf16 v[64:79], v[212:215], v[116:119], v[64:79]
	s_nop 10
	v_min_f32_e32 v80, 0x41f00000, v80
	v_exp_f32_e32 v160, v80
	v_min_f32_e32 v80, 0x41f00000, v82
	v_exp_f32_e32 v163, v80
	v_min_f32_e32 v80, 0x41f00000, v83
	v_exp_f32_e32 v161, v80
	v_min_f32_e32 v80, 0x41f00000, v84
	v_exp_f32_e32 v164, v80
	v_mfma_f32_32x32x16_bf16 v[64:79], v[208:211], v[120:123], v[64:79]
	v_min_f32_e32 v80, 0x41f00000, v85
	v_exp_f32_e32 v166, v80
	v_min_f32_e32 v80, 0x41f00000, v86
	v_exp_f32_e32 v167, v80
	v_min_f32_e32 v80, 0x41f00000, v87
	v_exp_f32_e32 v165, v80
	v_min_f32_e32 v80, 0x41f00000, v88
	v_exp_f32_e32 v88, v80
	v_mfma_f32_32x32x16_bf16 v[64:79], v[216:219], v[124:127], v[64:79]
	v_min_f32_e32 v80, 0x41f00000, v89
	v_exp_f32_e32 v168, v80
	v_min_f32_e32 v80, 0x41f00000, v90
	v_exp_f32_e32 v169, v80
	v_min_f32_e32 v80, 0x41f00000, v91
	v_mfma_f32_32x32x16_bf16 v[32:47], v[140:143], v[220:223], v[32:47]
	v_exp_f32_e32 v89, v80
	v_min_f32_e32 v80, 0x41f00000, v92
	v_exp_f32_e32 v90, v80
	v_min_f32_e32 v80, 0x41f00000, v93
	s_nop 1
	v_min_f32_e32 v64, 0x41f00000, v64
	v_exp_f32_e32 v92, v80
	v_min_f32_e32 v80, 0x41f00000, v94
	v_exp_f32_e32 v94, v64
	v_min_f32_e32 v64, 0x41f00000, v65
	v_exp_f32_e32 v170, v64
	v_mfma_f32_32x32x16_bf16 v[32:47], v[136:139], v[224:227], v[32:47]
	v_min_f32_e32 v64, 0x41f00000, v66
	v_exp_f32_e32 v171, v64
	v_min_f32_e32 v64, 0x41f00000, v67
	v_exp_f32_e32 v93, v80
	v_min_f32_e32 v80, 0x41f00000, v95
	v_exp_f32_e32 v95, v64
	v_min_f32_e32 v64, 0x41f00000, v68
	v_exp_f32_e32 v172, v64
	v_min_f32_e32 v64, 0x41f00000, v69
	v_exp_f32_e32 v174, v64
	v_mfma_f32_32x32x16_bf16 v[32:47], v[132:135], v[228:231], v[32:47]
	v_min_f32_e32 v64, 0x41f00000, v70
	v_exp_f32_e32 v175, v64
	v_min_f32_e32 v81, 0x41f00000, v81
	v_min_f32_e32 v64, 0x41f00000, v71
	v_min_f32_e32 v73, 0x41f00000, v73
	v_exp_f32_e32 v162, v81
	v_exp_f32_e32 v91, v80
	v_exp_f32_e32 v173, v64
	ds_read_b64_tr_b16 v[84:85], v149 offset:32768
	ds_read_b64_tr_b16 v[80:81], v149 offset:36864
	ds_read_b64_tr_b16 v[68:69], v149 offset:40960
	ds_read_b64_tr_b16 v[64:65], v149 offset:45056
	ds_read_b64_tr_b16 v[86:87], v176 offset:34816
	ds_read_b64_tr_b16 v[82:83], v176 offset:38912
	ds_read_b64_tr_b16 v[70:71], v176 offset:43008
	ds_read_b64_tr_b16 v[66:67], v176 offset:47104
	v_exp_f32_e32 v176, v73
	v_min_f32_e32 v73, 0x41f00000, v74
	v_exp_f32_e32 v177, v73
	v_min_f32_e32 v73, 0x41f00000, v75
	v_min_f32_e32 v75, 0x41f00000, v77
	v_min_f32_e32 v74, 0x41f00000, v76
	v_exp_f32_e32 v76, v75
	v_mfma_f32_32x32x16_bf16 v[32:47], v[128:131], v[232:235], v[32:47]
	v_min_f32_e32 v75, 0x41f00000, v78
	v_exp_f32_e32 v77, v75
	v_min_f32_e32 v72, 0x41f00000, v72
	v_min_f32_e32 v75, 0x41f00000, v79
	v_exp_f32_e32 v72, v72
	v_exp_f32_e32 v73, v73
	v_exp_f32_e32 v74, v74
	v_exp_f32_e32 v75, v75
	s_cbranch_scc1 .LBB0_606
; __device__ __forceinline__ int crow(int r, int hi) { return (r & 3) + 8 * (r >> 2) + 4 * hi; }
; #define ATT_SB() do {} while (0)
; #define ATT_SB() do {} while (0)
; #define ATT_SB() __builtin_amdgcn_sched_barrier(0)
; #define ATT_PV(f) do { if (DO_PV) { o[(f) >> 2] = __builtin_amdgcn_mfma_f32_32x32x16_bf16(pa[(f) & 3], vf[f], o[(f) >> 2], 0, 0, 0); if ((f) + 4 < 16) ATT_VLD((f) + 4); } } while (0)
; #define ATT_LBLK(j) do { const int ph_ = 1 - ((j) >> 2), g_ = 3 - ((j) & 3); \
;         const float w0_ = 1.0f + p[ph_][4 * g_], w1_ = 1.0f + p[ph_][4 * g_ + 1], w2_ = 1.0f + p[ph_][4 * g_ + 2], w3_ = 1.0f + p[ph_][4 * g_ + 3]; \
;         L[j] = __builtin_amdgcn_logf((w0_ * w1_) * (w2_ * w3_)); } while (0)
; template <bool DO_PV> ...
;     ...
;     if (need_mask) {
; #pragma unroll
;         for (int ph = 0; ph < 2; ++ph)
; #pragma unroll
;             for (int r = 0; r < 16; ++r) { const int key = k0 + 32 * ph + crow(r, hi); if (key >= qabs) p[ph][r] = 0.f; }
;     }
;     ATT_SB();
;     ATT_PV(4); ATT_LBLK(0); ATT_LBLK(1); ATT_SB();
;     ATT_PV(5); ATT_LBLK(2); ATT_LBLK(3); ATT_SB();
;     ATT_PV(6); ATT_LBLK(4); ATT_LBLK(5); ATT_SB();
;     ATT_PV(7); ATT_LBLK(6); ATT_LBLK(7); ATT_SB();
	v_add_u32_e32 v78, s65, v187
	v_add_u32_e32 v79, 1, v78
	v_cmp_lt_i32_e32 vcc, v78, v144
	v_cmp_lt_i32_e64 s[4:5], v79, v144
	s_or_b64 vcc, s[4:5], vcc
	v_add_u32_e32 v79, 2, v78
	v_cndmask_b32_e32 v160, 0, v160, vcc
	v_cmp_lt_i32_e32 vcc, v79, v144
	v_add_u32_e32 v79, 3, v78
	v_cndmask_b32_e64 v162, 0, v162, s[4:5]
	v_cndmask_b32_e32 v163, 0, v163, vcc
	v_cmp_lt_i32_e32 vcc, v79, v144
	v_add_u32_e32 v79, 8, v78
	s_nop 0
	v_cndmask_b32_e32 v161, 0, v161, vcc
	v_cmp_lt_i32_e32 vcc, v79, v144
	v_add_u32_e32 v79, 9, v78
	s_nop 0
	v_cndmask_b32_e32 v164, 0, v164, vcc
	v_cmp_lt_i32_e32 vcc, v79, v144
	v_add_u32_e32 v79, 10, v78
	s_nop 0
	v_cndmask_b32_e32 v166, 0, v166, vcc
	v_cmp_lt_i32_e32 vcc, v79, v144
	v_add_u32_e32 v79, 11, v78
	s_nop 0
	v_cndmask_b32_e32 v167, 0, v167, vcc
	v_cmp_lt_i32_e32 vcc, v79, v144
	v_add_u32_e32 v79, 16, v78
	s_nop 0
	v_cndmask_b32_e32 v165, 0, v165, vcc
	v_cmp_lt_i32_e32 vcc, v79, v144
	v_add_u32_e32 v79, 17, v78
	s_nop 0
	v_cndmask_b32_e32 v88, 0, v88, vcc
	v_cmp_lt_i32_e32 vcc, v79, v144
	v_add_u32_e32 v79, 18, v78
	s_nop 0
	v_cndmask_b32_e32 v168, 0, v168, vcc
	v_cmp_lt_i32_e32 vcc, v79, v144
	v_add_u32_e32 v79, 19, v78
	s_nop 0
	v_cndmask_b32_e32 v169, 0, v169, vcc
	v_cmp_lt_i32_e32 vcc, v79, v144
	v_add_u32_e32 v79, 24, v78
	s_nop 0
	v_cndmask_b32_e32 v89, 0, v89, vcc
	v_cmp_lt_i32_e32 vcc, v79, v144
	v_add_u32_e32 v79, 25, v78
	s_nop 0
	v_cndmask_b32_e32 v90, 0, v90, vcc
	v_cmp_lt_i32_e32 vcc, v79, v144
	v_add_u32_e32 v79, 26, v78
	s_nop 0
	v_cndmask_b32_e32 v92, 0, v92, vcc
	v_cmp_lt_i32_e32 vcc, v79, v144
	v_add_u32_e32 v79, 27, v78
	s_nop 0
	v_cndmask_b32_e32 v93, 0, v93, vcc
	v_cmp_lt_i32_e32 vcc, v79, v144
	v_add_u32_e32 v79, 32, v78
	v_cmp_lt_i32_e64 s[4:5], v79, v144
	v_add_u32_e32 v79, 33, v78
	v_cmp_lt_i32_e64 s[6:7], v79, v144
	v_add_u32_e32 v79, 34, v78
	v_cmp_lt_i32_e64 s[8:9], v79, v144
	v_add_u32_e32 v79, 35, v78
	v_cmp_lt_i32_e64 s[10:11], v79, v144
	v_add_u32_e32 v79, 40, v78
	v_cmp_lt_i32_e64 s[12:13], v79, v144
	v_add_u32_e32 v79, 41, v78
	v_cmp_lt_i32_e64 s[14:15], v79, v144
	v_add_u32_e32 v79, 42, v78
	v_cmp_lt_i32_e64 s[16:17], v79, v144
	v_add_u32_e32 v79, 43, v78
	v_cmp_lt_i32_e64 s[18:19], v79, v144
	v_add_u32_e32 v79, 48, v78
	v_cmp_lt_i32_e64 s[20:21], v79, v144
	v_add_u32_e32 v79, 49, v78
	v_cmp_lt_i32_e64 s[22:23], v79, v144
	v_add_u32_e32 v79, 50, v78
	v_cmp_lt_i32_e64 s[24:25], v79, v144
	v_add_u32_e32 v79, 51, v78
	v_cmp_lt_i32_e64 s[26:27], v79, v144
	v_add_u32_e32 v79, 56, v78
	v_cmp_lt_i32_e64 s[28:29], v79, v144
	v_add_u32_e32 v79, 57, v78
	v_cmp_lt_i32_e64 s[30:31], v79, v144
	v_add_u32_e32 v79, 58, v78
	v_add_u32_e32 v78, 59, v78
	v_cmp_lt_i32_e64 s[34:35], v79, v144
	v_cmp_lt_i32_e64 s[36:37], v78, v144
	s_or_b64 s[34:35], s[36:37], s[34:35]
	s_or_b64 s[30:31], s[34:35], s[30:31]
	s_or_b64 s[28:29], s[30:31], s[28:29]
	s_or_b64 s[26:27], s[28:29], s[26:27]
	s_or_b64 s[24:25], s[26:27], s[24:25]
	s_or_b64 s[22:23], s[24:25], s[22:23]
	s_or_b64 s[20:21], s[22:23], s[20:21]
	s_or_b64 s[18:19], s[20:21], s[18:19]
	s_or_b64 s[16:17], s[18:19], s[16:17]
	s_or_b64 s[14:15], s[16:17], s[14:15]
	s_or_b64 s[12:13], s[14:15], s[12:13]
	s_or_b64 s[10:11], s[12:13], s[10:11]
	s_or_b64 s[8:9], s[10:11], s[8:9]
	s_or_b64 s[6:7], s[8:9], s[6:7]
	s_or_b64 s[4:5], s[6:7], s[4:5]
	s_or_b64 vcc, s[4:5], vcc
	v_cndmask_b32_e64 v75, 0, v75, s[36:37]
	v_cndmask_b32_e64 v77, 0, v77, s[34:35]
	v_cndmask_b32_e64 v76, 0, v76, s[30:31]
	v_cndmask_b32_e64 v74, 0, v74, s[28:29]
	v_cndmask_b32_e64 v73, 0, v73, s[26:27]
	v_cndmask_b32_e64 v177, 0, v177, s[24:25]
	v_cndmask_b32_e64 v176, 0, v176, s[22:23]
	v_cndmask_b32_e64 v72, 0, v72, s[20:21]
	v_cndmask_b32_e64 v173, 0, v173, s[18:19]
	v_cndmask_b32_e64 v175, 0, v175, s[16:17]
	v_cndmask_b32_e64 v174, 0, v174, s[14:15]
	v_cndmask_b32_e64 v172, 0, v172, s[12:13]
	v_cndmask_b32_e64 v95, 0, v95, s[10:11]
	v_cndmask_b32_e64 v171, 0, v171, s[8:9]
	v_cndmask_b32_e64 v170, 0, v170, s[6:7]
	v_cndmask_b32_e64 v94, 0, v94, s[4:5]
	v_cndmask_b32_e32 v91, 0, v91, vcc
.LBB0_606:
	s_waitcnt lgkmcnt(0)
	v_mfma_f32_32x32x16_bf16 v[48:63], v[140:143], v[84:87], v[48:63]
	v_add_f32_e64 v196, v76, 1.0
	v_add_f32_e64 v197, v77, 1.0
	v_add_f32_e64 v198, v74, 1.0
	v_add_f32_e64 v199, v75, 1.0
	v_add_f32_e64 v86, v176, 1.0
	v_add_f32_e64 v87, v177, 1.0
	v_mul_f32_e32 v78, v196, v198
	v_mul_f32_e32 v79, v197, v199
	v_add_f32_e32 v200, 1.0, v72
	v_add_f32_e32 v201, 1.0, v73
	v_mul_f32_e32 v78, v78, v79
	v_log_f32_e32 v199, v78
	v_mfma_f32_32x32x16_bf16 v[48:63], v[136:139], v[80:83], v[48:63]
	v_mul_f32_e64 v78, v86, v200
	v_mul_f32_e64 v79, v87, v201
	v_add_f32_e64 v202, v174, 1.0
	v_add_f32_e64 v203, v175, 1.0
	v_mul_f32_e32 v78, v78, v79
	v_add_f32_e32 v204, 1.0, v172
	v_add_f32_e32 v205, 1.0, v173
	v_add_f32_e32 v210, 1.0, v92
	v_add_f32_e32 v211, 1.0, v93
	v_add_f32_e32 v212, 1.0, v90
	v_add_f32_e32 v213, 1.0, v91
	v_log_f32_e32 v201, v78
	v_mfma_f32_32x32x16_bf16 v[48:63], v[132:135], v[68:71], v[48:63]
	v_mul_f32_e64 v78, v202, v204
	v_mul_f32_e64 v79, v203, v205
	v_mul_f32_e64 v68, v210, v212
	v_mul_f32_e64 v69, v211, v213
	v_mul_f32_e32 v78, v78, v79
	v_add_f32_e32 v206, 1.0, v170
	v_add_f32_e32 v207, 1.0, v171
	v_add_f32_e32 v208, 1.0, v94
	v_add_f32_e32 v209, 1.0, v95
	v_mul_f32_e32 v68, v68, v69
	v_add_f32_e32 v214, 1.0, v168
	v_add_f32_e32 v215, 1.0, v169
	v_add_f32_e32 v216, 1.0, v88
	v_add_f32_e32 v217, 1.0, v89
	v_log_f32_e32 v205, v78
	v_mul_f32_e32 v78, v206, v208
	v_mul_f32_e32 v79, v207, v209
	v_log_f32_e32 v213, v68
	v_mul_f32_e32 v68, v214, v216
	v_mul_f32_e32 v69, v215, v217
	v_add_u32_e32 v149, v194, v192
	v_mul_f32_e32 v78, v78, v79
	v_mul_f32_e32 v68, v68, v69
	v_add_u32_e32 v218, v159, v192
	v_log_f32_e32 v209, v78
	v_log_f32_e32 v217, v68
	v_mfma_f32_32x32x16_bf16 v[48:63], v[128:131], v[64:67], v[48:63]
	ds_read_b64_tr_b16 v[64:65], v149 offset:32768
	ds_read_b64_tr_b16 v[68:69], v149 offset:36864
	ds_read_b64_tr_b16 v[78:79], v149 offset:40960
	ds_read_b64_tr_b16 v[82:83], v149 offset:45056
	ds_read_b64_tr_b16 v[66:67], v218 offset:34816
	ds_read_b64_tr_b16 v[70:71], v218 offset:38912
	ds_read_b64_tr_b16 v[80:81], v218 offset:43008
	ds_read_b64_tr_b16 v[84:85], v218 offset:47104
	v_add_f32_e32 v218, 1.0, v166
	v_add_f32_e32 v219, 1.0, v167
	v_add_f32_e32 v220, 1.0, v164
	v_add_f32_e32 v221, 1.0, v165
	v_add_f32_e32 v224, 1.0, v160
	v_add_f32_e32 v225, 1.0, v161
	v_mul_f32_e32 v222, v218, v220
	v_mul_f32_e32 v223, v219, v221
	v_add_u32_e32 v194, v194, v193
	v_mul_f32_e32 v149, v222, v223
	s_waitcnt lgkmcnt(0)
; __device__ __forceinline__ unsigned pk_bf16(float lo, float hi) { return pg8::cvt_pk_bf16(lo, hi); }
; #define ATT_SB() do {} while (0)
; #define ATT_SB() do {} while (0)
; #define ATT_SB() __builtin_amdgcn_sched_barrier(0)
; #define ATT_PV(f) do { if (DO_PV) { o[(f) >> 2] = __builtin_amdgcn_mfma_f32_32x32x16_bf16(pa[(f) & 3], vf[f], o[(f) >> 2], 0, 0, 0); if ((f) + 4 < 16) ATT_VLD((f) + 4); } } while (0)
; #define ATT_XCH(j) do { const float own_ = L[j]; const auto rr_ = __builtin_amdgcn_permlane32_swap(__float_as_uint(own_), __float_as_uint(own_), false, false); \
;         const float a0_ = __uint_as_float(rr_[0]), a1_ = __uint_as_float(rr_[1]); const float oth_ = (a0_ == own_) ? a1_ : a0_; \
;         T[j] = run + (hi ? 0.f : oth_) + own_; run += a0_ + a1_; } while (0)
; #define ATT_WGT(j) do { const int ph_ = 1 - ((j) >> 2), g_ = 3 - ((j) & 3); float cf_ = __builtin_amdgcn_exp2f(-T[j]); \
;         _Pragma("unroll") for (int e_ = 0; e_ < 4; ++e_) { const float ev_ = p[ph_][4 * g_ + e_]; p[ph_][4 * g_ + e_] = ev_ * cf_; if (e_ < 3) cf_ *= (1.0f + ev_); } } while (0)
; template <bool DO_PV> ...
;     ...
;     float run = carry;
;     ATT_PV(8); ATT_XCH(0); ATT_XCH(1); ATT_SB();
;     ATT_PV(9); ATT_XCH(2); ATT_XCH(3); ATT_SB();
;     ATT_PV(10); ATT_XCH(4); ATT_XCH(5); ATT_SB();
;     ATT_PV(11); ATT_XCH(6); ATT_XCH(7); ATT_SB();
;     carry = run;
;     ATT_PV(12); ATT_WGT(0); ATT_WGT(1); ATT_SB();
;     ATT_PV(13); ATT_WGT(2); ATT_WGT(3); ATT_SB();
;     ATT_PV(14); ATT_WGT(4); ATT_WGT(5); ATT_SB();
;     ATT_PV(15); ATT_WGT(6); ATT_WGT(7); ATT_SB();
; #pragma unroll
;     for (int s = 0; s < 4; ++s) { const int ph = s >> 1, rb = 8 * (s & 1);
;         u32x4 w; w.x = pk_bf16(p[ph][rb], p[ph][rb + 1]); w.y = pk_bf16(p[ph][rb + 2], p[ph][rb + 3]); w.z = pk_bf16(p[ph][rb + 4], p[ph][rb + 5]); w.w = pk_bf16(p[ph][rb + 6], p[ph][rb + 7]);
;         pa[s] = __builtin_bit_cast(bf16x8, w); }
	v_mfma_f32_32x32x16_bf16 v[0:15], v[140:143], v[64:67], v[0:15]
	v_mov_b32_e32 v64, v199
	v_mov_b32_e32 v65, v199
	s_nop 1
	v_permlane32_swap_b32_e32 v64, v65
	v_add_f32_e64 v222, v162, 1.0
	v_add_f32_e64 v223, v163, 1.0
	v_cmp_eq_f32_e32 vcc, v199, v64
	v_mul_f32_e32 v226, v222, v224
	v_mul_f32_e32 v227, v223, v225
	v_add_u32_e32 v225, v159, v193
	v_cndmask_b32_e32 v66, v64, v65, vcc
	v_add_f32_e32 v64, v64, v65
	v_mov_b32_e32 v159, v201
	v_mov_b32_e32 v65, v201
	v_cndmask_b32_e64 v66, 0, v66, s[0:1]
	s_nop 0
	v_permlane32_swap_b32_e32 v159, v65
	v_add_f32_e32 v66, v158, v66
	v_cmp_eq_f32_e32 vcc, v201, v159
	v_add_f32_e32 v199, v199, v66
	v_mfma_f32_32x32x16_bf16 v[0:15], v[136:139], v[68:71], v[0:15]
	v_cndmask_b32_e32 v66, v159, v65, vcc
	v_cndmask_b32_e64 v66, 0, v66, s[0:1]
	v_add_f32_e64 v64, v158, v64
	v_add_f32_e64 v65, v159, v65
	v_exp_f32_e64 v199, -v199
	v_add_f32_e32 v228, v64, v66
	v_add_f32_e32 v64, v64, v65
	v_mov_b32_e32 v65, v64
	v_mov_b32_e32 v66, v205
	v_mov_b32_e32 v65, v205
	s_nop 1
	v_permlane32_swap_b32_e32 v65, v66
	v_cmp_eq_f32_e32 vcc, v205, v65
	v_mfma_f32_32x32x16_bf16 v[0:15], v[132:135], v[78:81], v[0:15]
	v_log_f32_e32 v149, v149
	v_cndmask_b32_e32 v67, v65, v66, vcc
	v_cndmask_b32_e64 v67, 0, v67, s[0:1]
	v_add_f32_e32 v229, v64, v67
	v_add_f32_e32 v66, v65, v66
	v_mov_b32_e32 v65, v209
	v_mov_b32_e32 v67, v209
	s_nop 1
	v_permlane32_swap_b32_e32 v65, v67
	v_cmp_eq_f32_e32 vcc, v209, v65
	v_mfma_f32_32x32x16_bf16 v[0:15], v[128:131], v[82:85], v[0:15]
	v_mul_f32_e32 v221, v226, v227
	v_cndmask_b32_e32 v68, v65, v67, vcc
	v_cndmask_b32_e64 v68, 0, v68, s[0:1]
	v_add_f32_e64 v64, v64, v66
	v_add_f32_e64 v65, v65, v67
	v_mov_b32_e32 v66, v213
	v_add_f32_e32 v230, v64, v68
	v_add_f32_e32 v64, v64, v65
	v_mov_b32_e32 v65, v64
	v_log_f32_e32 v221, v221
	v_mov_b32_e32 v65, v213
	s_nop 1
	v_permlane32_swap_b32_e32 v65, v66
	v_cmp_eq_f32_e32 vcc, v213, v65
	v_mov_b32_e32 v227, v221
	s_nop 0
	v_cndmask_b32_e32 v67, v65, v66, vcc
	v_cndmask_b32_e64 v67, 0, v67, s[0:1]
	v_add_f32_e32 v231, v64, v67
	v_add_f32_e32 v66, v65, v66
	v_mov_b32_e32 v65, v217
	v_mov_b32_e32 v67, v217
	s_nop 1
	v_permlane32_swap_b32_e32 v65, v67
	v_cmp_eq_f32_e32 vcc, v217, v65
	s_nop 1
	v_cndmask_b32_e32 v68, v65, v67, vcc
	v_cndmask_b32_e64 v68, 0, v68, s[0:1]
	v_add_f32_e32 v64, v64, v66
	v_add_f32_e32 v65, v65, v67
	s_nop 0
	v_add_f32_e32 v232, v64, v68
	v_add_f32_e32 v158, v64, v65
	v_add_f32_e32 v159, v65, v64
	ds_read_b64_tr_b16 v[64:65], v194 offset:32768
	ds_read_b64_tr_b16 v[68:69], v194 offset:36864
	ds_read_b64_tr_b16 v[78:79], v194 offset:40960
	ds_read_b64_tr_b16 v[82:83], v194 offset:45056
	ds_read_b64_tr_b16 v[66:67], v225 offset:34816
	ds_read_b64_tr_b16 v[70:71], v225 offset:38912
	ds_read_b64_tr_b16 v[80:81], v225 offset:43008
	ds_read_b64_tr_b16 v[84:85], v225 offset:47104
	s_waitcnt lgkmcnt(0)
	v_mfma_f32_32x32x16_bf16 v[16:31], v[140:143], v[64:67], v[16:31]
	v_mul_f32_e32 v64, v198, v199
	v_mul_f32_e32 v141, v76, v64
	v_mul_f32_e32 v64, v196, v64
	v_mul_f32_e32 v142, v77, v64
	v_mul_f32_e32 v64, v197, v64
	v_mul_f32_e32 v143, v75, v64
	v_add_f32_e32 v64, v201, v228
	v_exp_f32_e64 v64, -v64
	v_add_f32_e32 v65, v205, v229
	v_exp_f32_e64 v65, -v65
	v_mul_f32_e32 v140, v74, v199
	v_mul_f32_e32 v76, v72, v64
	v_mul_f32_e32 v64, v200, v64
	v_mul_f32_e32 v77, v176, v64
	v_mul_f32_e32 v64, v86, v64
	v_mul_f32_e32 v86, v177, v64
	v_mul_f32_e32 v64, v87, v64
	v_mul_f32_e32 v87, v73, v64
	v_add_f32_e32 v64, v209, v230
	v_mul_f32_e32 v74, v172, v65
	v_mul_f32_e32 v65, v204, v65
	v_mfma_f32_32x32x16_bf16 v[16:31], v[136:139], v[68:71], v[16:31]
	v_mul_f32_e32 v75, v174, v65
	v_mul_f32_e32 v65, v202, v65
	v_exp_f32_e64 v64, -v64
	v_mul_f32_e32 v136, v175, v65
	v_mul_f32_e32 v65, v203, v65
	v_mul_f32_e32 v137, v173, v65
	v_add_f32_e32 v65, v213, v231
	v_exp_f32_e64 v65, -v65
	v_mov_b32_e32 v159, v149
	v_mov_b32_e32 v194, v149
	v_mul_f32_e32 v72, v94, v64
	v_mul_f32_e32 v64, v208, v64
	v_permlane32_swap_b32_e32 v159, v194
	v_mul_f32_e32 v73, v170, v64
	v_mul_f32_e32 v64, v206, v64
	v_cmp_eq_f32_e32 vcc, v149, v159
	v_add_f32_e32 v66, v217, v232
	v_mul_f32_e32 v94, v171, v64
	v_mul_f32_e32 v64, v207, v64
	v_cndmask_b32_e32 v225, v159, v194, vcc
	v_mul_f32_e32 v95, v95, v64
	v_mul_f32_e32 v70, v90, v65
	v_mul_f32_e32 v64, v212, v65
	v_exp_f32_e64 v65, -v66
	v_cndmask_b32_e64 v225, 0, v225, s[0:1]
	v_mfma_f32_32x32x16_bf16 v[16:31], v[132:135], v[78:81], v[16:31]
	v_add_f32_e32 v225, v158, v225
	v_add_f32_e32 v226, v159, v194
	v_mov_b32_e32 v159, v221
	v_mul_f32_e32 v71, v92, v64
	v_mul_f32_e32 v64, v210, v64
	v_permlane32_swap_b32_e32 v159, v227
	v_add_f32_e32 v67, v149, v225
	v_mul_f32_e32 v78, v93, v64
	v_mul_f32_e32 v64, v211, v64
	v_cmp_eq_f32_e32 vcc, v221, v159
	v_mul_f32_e32 v79, v91, v64
	v_mul_f32_e32 v68, v88, v65
	v_mul_f32_e32 v64, v216, v65
	v_exp_f32_e64 v65, -v67
	v_cndmask_b32_e32 v194, v159, v227, vcc
	v_cndmask_b32_e64 v194, 0, v194, s[0:1]
	v_add_f32_e32 v158, v158, v226
	v_add_f32_e32 v159, v159, v227
	v_mul_f32_e32 v69, v168, v64
	v_mul_f32_e32 v64, v214, v64
	v_add_f32_e32 v194, v158, v194
	v_mul_f32_e32 v80, v169, v64
	v_mul_f32_e32 v64, v215, v64
	v_mul_f32_e32 v81, v89, v64
	v_mul_f32_e32 v66, v164, v65
	v_mul_f32_e32 v64, v220, v65
	v_add_f32_e32 v65, v221, v194
	v_mfma_f32_32x32x16_bf16 v[16:31], v[128:131], v[82:85], v[16:31]
	v_exp_f32_e64 v65, -v65
	v_mul_f32_e32 v67, v166, v64
	v_mul_f32_e32 v64, v218, v64
	v_mul_f32_e32 v82, v167, v64
	v_mul_f32_e32 v64, v219, v64
	v_mul_f32_e32 v83, v165, v64
	v_mul_f32_e32 v64, v160, v65
	v_mul_f32_e32 v65, v224, v65
	v_mul_f32_e32 v84, v162, v65
	v_mul_f32_e32 v65, v222, v65
	v_mul_f32_e32 v85, v163, v65
	v_mul_f32_e32 v65, v223, v65
	v_add_f32_e32 v159, v158, v159
	v_mul_f32_e32 v65, v161, v65
	v_cvt_pk_bf16_f32 v64, v64, v84
	v_cvt_pk_bf16_f32 v65, v85, v65
	v_cvt_pk_bf16_f32 v66, v66, v67
	v_cvt_pk_bf16_f32 v67, v82, v83
	v_cvt_pk_bf16_f32 v68, v68, v69
	v_cvt_pk_bf16_f32 v69, v80, v81
	v_cvt_pk_bf16_f32 v70, v70, v71
	v_cvt_pk_bf16_f32 v71, v78, v79
	v_cvt_pk_bf16_f32 v72, v72, v73
	v_cvt_pk_bf16_f32 v73, v94, v95
	v_cvt_pk_bf16_f32 v74, v74, v75
	v_cvt_pk_bf16_f32 v75, v136, v137
	v_cvt_pk_bf16_f32 v76, v76, v77
	v_cvt_pk_bf16_f32 v77, v86, v87
	v_cvt_pk_bf16_f32 v78, v140, v141
	v_cvt_pk_bf16_f32 v79, v142, v143

; #define LAS __attribute__((address_space(3)))
; #define ATT_SB() do {} while (0)
; #define ATT_SB() do {} while (0)
; #define ATT_SB() __builtin_amdgcn_sched_barrier(0)
; #define ATT_VLD(f) do { const int c_ = (f) >> 2, s_ = (f) & 3; const s16x4 lo_ = vtr(vbp + 4096 * s_ + vbase[0] + vcq[c_]); const s16x4 hh_ = vtr(vbp + 4096 * s_ + vbase[1] + vcq[c_]); \
;         vf[f] = (bf16x8){lo_[0], lo_[1], lo_[2], lo_[3], hh_[0], hh_[1], hh_[2], hh_[3]}; } while (0)
; #define ATT_PV(f) do { if (DO_PV) { o[(f) >> 2] = __builtin_amdgcn_mfma_f32_32x32x16_bf16(pa[(f) & 3], vf[f], o[(f) >> 2], 0, 0, 0); if ((f) + 4 < 16) ATT_VLD((f) + 4); } } while (0)
; #define ATT_EXP8(i) do { _Pragma("unroll") for (int r_ = 0; r_ < 8; ++r_) p[(i) >> 1][8 * ((i) & 1) + r_] = __builtin_amdgcn_exp2f(fminf(p[(i) >> 1][8 * ((i) & 1) + r_], 30.f)); } while (0)
; template <bool DO_PV> ...
;     f32x16 p[2];
; #pragma unroll
;     for (int r = 0; r < 16; ++r) { p[0][r] = 0.f; p[1][r] = 0.f; }
;     bf16x8 vf[16];
;     if (DO_PV) { ATT_VLD(0); ATT_VLD(1); ATT_VLD(2); ATT_VLD(3); }
;     {
;         bf16x8 ka[8], kc[8];
; #pragma unroll
;         for (int d0 = 0; d0 < 8; ++d0) { ka[d0] = *(const LAS bf16x8*)(kb + koff[d0]); kc[d0] = *(const LAS bf16x8*)(kb + 8192 + koff[d0]); }
;         ATT_SB();
; #pragma unroll
;         for (int d0 = 0; d0 < 8; ++d0) {
;             p[0] = __builtin_amdgcn_mfma_f32_32x32x16_bf16(ka[d0], qf[d0], p[0], 0, 0, 0);
;             p[1] = __builtin_amdgcn_mfma_f32_32x32x16_bf16(kc[d0], qf[d0], p[1], 0, 0, 0);
;         }
;     }
;     ATT_SB();
;     const bool need_mask = (k0 + 63 >= qw0);
;     float L[8], T[8];
;     ATT_PV(0); ATT_EXP8(0); ATT_SB();
;     ATT_PV(1); ATT_EXP8(1); ATT_SB();
;     ATT_PV(2); ATT_EXP8(2); ATT_SB();
;     ATT_PV(3); ATT_EXP8(3); ATT_SB();
.LBB0_615:
	s_sub_i32 s6, s66, 63
	s_cmp_lt_i32 s6, s65
	s_cselect_b64 s[52:53], -1, 0
	s_cmp_ge_i32 s6, s65
	s_cbranch_scc1 .LBB0_625
	s_xor_b64 s[6:7], s[4:5], -1
	s_add_i32 s8, s8, 0
	s_mov_b64 s[4:5], -1
	s_and_b64 vcc, exec, s[6:7]
	v_add_u32_e32 v168, s8, v179
	v_add_u32_e32 v167, s8, v180
	v_add_u32_e32 v166, s8, v181
	v_add_u32_e32 v165, s8, v182
	v_add_u32_e32 v164, s8, v183
	v_add_u32_e32 v163, s8, v184
	v_add_u32_e32 v162, s8, v185
	v_add_u32_e32 v149, s8, v186
	s_cbranch_vccz .LBB0_620
	ds_read_b128 v[64:67], v168
	ds_read_b128 v[68:71], v168 offset:8192
	ds_read_b128 v[170:173], v167
	ds_read_b128 v[174:177], v167 offset:8192
	s_cmp_lt_i32 s66, s63
	s_waitcnt lgkmcnt(0)
	v_mfma_f32_32x32x16_bf16 v[80:95], v[64:67], v[96:99], 0
	v_mfma_f32_32x32x16_bf16 v[80:95], v[170:173], v[100:103], v[80:95]
	ds_read_b128 v[170:173], v166
	ds_read_b128 v[196:199], v166 offset:8192
	v_mfma_f32_32x32x16_bf16 v[64:79], v[68:71], v[96:99], 0
	s_waitcnt lgkmcnt(0)
	v_mfma_f32_32x32x16_bf16 v[80:95], v[170:173], v[104:107], v[80:95]
	ds_read_b128 v[170:173], v165
	ds_read_b128 v[200:203], v165 offset:8192
	v_mfma_f32_32x32x16_bf16 v[64:79], v[174:177], v[100:103], v[64:79]
	s_waitcnt lgkmcnt(0)
	v_mfma_f32_32x32x16_bf16 v[80:95], v[170:173], v[108:111], v[80:95]
	ds_read_b128 v[170:173], v164
	ds_read_b128 v[204:207], v164 offset:8192
	v_mfma_f32_32x32x16_bf16 v[64:79], v[196:199], v[104:107], v[64:79]
	s_waitcnt lgkmcnt(0)
	v_mfma_f32_32x32x16_bf16 v[80:95], v[170:173], v[112:115], v[80:95]
	ds_read_b128 v[170:173], v163
	ds_read_b128 v[208:211], v163 offset:8192
	v_mfma_f32_32x32x16_bf16 v[64:79], v[200:203], v[108:111], v[64:79]
	s_waitcnt lgkmcnt(0)
	v_mfma_f32_32x32x16_bf16 v[80:95], v[170:173], v[116:119], v[80:95]
	ds_read_b128 v[170:173], v162
	ds_read_b128 v[212:215], v162 offset:8192
	v_mfma_f32_32x32x16_bf16 v[64:79], v[204:207], v[112:115], v[64:79]
	s_waitcnt lgkmcnt(0)
	v_mfma_f32_32x32x16_bf16 v[80:95], v[170:173], v[120:123], v[80:95]
	ds_read_b128 v[170:173], v149
	ds_read_b128 v[216:219], v149 offset:8192
	v_mfma_f32_32x32x16_bf16 v[64:79], v[208:211], v[116:119], v[64:79]
	s_waitcnt lgkmcnt(0)
	v_mfma_f32_32x32x16_bf16 v[80:95], v[170:173], v[124:127], v[80:95]
	v_mfma_f32_32x32x16_bf16 v[64:79], v[212:215], v[120:123], v[64:79]
	s_nop 10
	v_min_f32_e32 v81, 0x41f00000, v81
	v_exp_f32_e32 v160, v81
	v_min_f32_e32 v81, 0x41f00000, v82
	v_exp_f32_e32 v161, v81
	v_min_f32_e32 v81, 0x41f00000, v83
	v_mfma_f32_32x32x16_bf16 v[64:79], v[216:219], v[124:127], v[64:79]
	v_min_f32_e32 v83, 0x41f00000, v85
	v_min_f32_e32 v82, 0x41f00000, v84
	v_exp_f32_e32 v84, v83
	v_min_f32_e32 v83, 0x41f00000, v86
	v_exp_f32_e32 v85, v83
	v_min_f32_e32 v83, 0x41f00000, v87
	v_min_f32_e32 v87, 0x41f00000, v89
	v_min_f32_e32 v86, 0x41f00000, v88
	v_exp_f32_e32 v88, v87
	v_min_f32_e32 v87, 0x41f00000, v90
	v_exp_f32_e32 v89, v87
	v_min_f32_e32 v87, 0x41f00000, v91
	v_min_f32_e32 v91, 0x41f00000, v93
	v_min_f32_e32 v65, 0x41f00000, v65
	v_min_f32_e32 v90, 0x41f00000, v92
	v_exp_f32_e32 v92, v91
	v_min_f32_e32 v91, 0x41f00000, v94
	v_exp_f32_e32 v94, v65
	v_min_f32_e32 v65, 0x41f00000, v66
	v_exp_f32_e32 v93, v91
	v_min_f32_e32 v91, 0x41f00000, v95
	v_exp_f32_e32 v95, v65
	v_min_f32_e32 v65, 0x41f00000, v67
	v_min_f32_e32 v67, 0x41f00000, v69
	v_min_f32_e32 v66, 0x41f00000, v68
	v_exp_f32_e32 v68, v67
	v_min_f32_e32 v67, 0x41f00000, v70
	v_exp_f32_e32 v69, v67
	v_min_f32_e32 v67, 0x41f00000, v71
	v_min_f32_e32 v71, 0x41f00000, v73
	v_min_f32_e32 v70, 0x41f00000, v72
	v_exp_f32_e32 v72, v71
	v_min_f32_e32 v71, 0x41f00000, v74
	v_exp_f32_e32 v73, v71
	v_min_f32_e32 v71, 0x41f00000, v75
	v_min_f32_e32 v75, 0x41f00000, v77
	v_min_f32_e32 v74, 0x41f00000, v76
	v_exp_f32_e32 v76, v75
	v_min_f32_e32 v75, 0x41f00000, v78
	v_exp_f32_e32 v77, v75
	v_min_f32_e32 v80, 0x41f00000, v80
	v_min_f32_e32 v64, 0x41f00000, v64
	v_min_f32_e32 v75, 0x41f00000, v79
	v_exp_f32_e32 v80, v80
	v_exp_f32_e32 v81, v81
	v_exp_f32_e32 v82, v82
	v_exp_f32_e32 v83, v83
	v_exp_f32_e32 v86, v86
	v_exp_f32_e32 v87, v87
	v_exp_f32_e32 v90, v90
	v_exp_f32_e32 v91, v91
	v_exp_f32_e32 v64, v64
	v_exp_f32_e32 v65, v65
	v_exp_f32_e32 v66, v66
	v_exp_f32_e32 v67, v67
	v_exp_f32_e32 v70, v70
	v_exp_f32_e32 v71, v71
	v_exp_f32_e32 v74, v74
	v_exp_f32_e32 v75, v75
	s_cbranch_scc1 .LBB0_619
; __device__ __forceinline__ int crow(int r, int hi) { return (r & 3) + 8 * (r >> 2) + 4 * hi; }
; template <bool DO_PV> ...
;     ...
;     if (need_mask) {
; #pragma unroll
;         for (int ph = 0; ph < 2; ++ph)
; #pragma unroll
;             for (int r = 0; r < 16; ++r) { const int key = k0 + 32 * ph + crow(r, hi); if (key >= qabs) p[ph][r] = 0.f; }
;     }
	v_add_u32_e32 v78, s66, v187
	v_subrev_u32_e32 v79, 63, v78
	v_cmp_lt_i32_e32 vcc, v79, v144
	v_subrev_u32_e32 v79, 62, v78
	v_cmp_lt_i32_e64 s[4:5], v79, v144
	s_or_b64 vcc, s[4:5], vcc
	v_subrev_u32_e32 v79, 61, v78
	v_cndmask_b32_e32 v80, 0, v80, vcc
	v_cmp_lt_i32_e32 vcc, v79, v144
	v_subrev_u32_e32 v79, 60, v78
	v_cndmask_b32_e64 v160, 0, v160, s[4:5]
	v_cndmask_b32_e32 v161, 0, v161, vcc
	v_cmp_lt_i32_e32 vcc, v79, v144
	v_subrev_u32_e32 v79, 55, v78
	s_nop 0
	v_cndmask_b32_e32 v81, 0, v81, vcc
	v_cmp_lt_i32_e32 vcc, v79, v144
	v_subrev_u32_e32 v79, 54, v78
	s_nop 0
	v_cndmask_b32_e32 v82, 0, v82, vcc
	v_cmp_lt_i32_e32 vcc, v79, v144
	v_subrev_u32_e32 v79, 53, v78
	s_nop 0
	v_cndmask_b32_e32 v84, 0, v84, vcc
	v_cmp_lt_i32_e32 vcc, v79, v144
	v_subrev_u32_e32 v79, 52, v78
	s_nop 0
	v_cndmask_b32_e32 v85, 0, v85, vcc
	v_cmp_lt_i32_e32 vcc, v79, v144
	v_subrev_u32_e32 v79, 47, v78
	s_nop 0
	v_cndmask_b32_e32 v83, 0, v83, vcc
	v_cmp_lt_i32_e32 vcc, v79, v144
	v_subrev_u32_e32 v79, 46, v78
	s_nop 0
	v_cndmask_b32_e32 v86, 0, v86, vcc
	v_cmp_lt_i32_e32 vcc, v79, v144
	v_subrev_u32_e32 v79, 45, v78
	s_nop 0
	v_cndmask_b32_e32 v88, 0, v88, vcc
	v_cmp_lt_i32_e32 vcc, v79, v144
	v_subrev_u32_e32 v79, 44, v78
	s_nop 0
	v_cndmask_b32_e32 v89, 0, v89, vcc
	v_cmp_lt_i32_e32 vcc, v79, v144
	v_subrev_u32_e32 v79, 39, v78
	s_nop 0
	v_cndmask_b32_e32 v87, 0, v87, vcc
	v_cmp_lt_i32_e32 vcc, v79, v144
	v_subrev_u32_e32 v79, 38, v78
	s_nop 0
	v_cndmask_b32_e32 v90, 0, v90, vcc
	v_cmp_lt_i32_e32 vcc, v79, v144
	v_subrev_u32_e32 v79, 37, v78
	s_nop 0
	v_cndmask_b32_e32 v92, 0, v92, vcc
	v_cmp_lt_i32_e32 vcc, v79, v144
	v_subrev_u32_e32 v79, 36, v78
	s_nop 0
	v_cndmask_b32_e32 v93, 0, v93, vcc
	v_cmp_lt_i32_e32 vcc, v79, v144
	v_subrev_u32_e32 v79, 31, v78
	v_cmp_lt_i32_e64 s[4:5], v79, v144
	v_subrev_u32_e32 v79, 30, v78
	v_cmp_lt_i32_e64 s[6:7], v79, v144
	v_subrev_u32_e32 v79, 29, v78
	v_cmp_lt_i32_e64 s[8:9], v79, v144
	v_subrev_u32_e32 v79, 28, v78
	v_cmp_lt_i32_e64 s[10:11], v79, v144
	v_subrev_u32_e32 v79, 23, v78
	v_cmp_lt_i32_e64 s[12:13], v79, v144
	v_subrev_u32_e32 v79, 22, v78
	v_cmp_lt_i32_e64 s[14:15], v79, v144
	v_subrev_u32_e32 v79, 21, v78
	v_cmp_lt_i32_e64 s[16:17], v79, v144
	v_subrev_u32_e32 v79, 20, v78
	v_cmp_lt_i32_e64 s[18:19], v79, v144
	v_add_u32_e32 v79, -15, v78
	v_cmp_lt_i32_e64 s[20:21], v79, v144
	v_add_u32_e32 v79, -14, v78
	v_cmp_lt_i32_e64 s[22:23], v79, v144
	v_add_u32_e32 v79, -13, v78
	v_cmp_lt_i32_e64 s[24:25], v79, v144
	v_add_u32_e32 v79, -12, v78
	v_cmp_lt_i32_e64 s[26:27], v79, v144
	v_add_u32_e32 v79, -7, v78
	v_cmp_lt_i32_e64 s[28:29], v79, v144
	v_add_u32_e32 v79, -6, v78
	v_cmp_lt_i32_e64 s[30:31], v79, v144
	v_add_u32_e32 v79, -5, v78
	v_add_u32_e32 v78, -4, v78
	v_cmp_lt_i32_e64 s[34:35], v79, v144
	v_cmp_lt_i32_e64 s[36:37], v78, v144
	s_or_b64 s[34:35], s[36:37], s[34:35]
	s_or_b64 s[30:31], s[34:35], s[30:31]
	s_or_b64 s[28:29], s[30:31], s[28:29]
	s_or_b64 s[26:27], s[28:29], s[26:27]
	s_or_b64 s[24:25], s[26:27], s[24:25]
	s_or_b64 s[22:23], s[24:25], s[22:23]
	s_or_b64 s[20:21], s[22:23], s[20:21]
	s_or_b64 s[18:19], s[20:21], s[18:19]
	s_or_b64 s[16:17], s[18:19], s[16:17]
	s_or_b64 s[14:15], s[16:17], s[14:15]
	s_or_b64 s[12:13], s[14:15], s[12:13]
	s_or_b64 s[10:11], s[12:13], s[10:11]
	s_or_b64 s[8:9], s[10:11], s[8:9]
	s_or_b64 s[6:7], s[8:9], s[6:7]
	s_or_b64 s[4:5], s[6:7], s[4:5]
	s_or_b64 vcc, s[4:5], vcc
	v_cndmask_b32_e64 v75, 0, v75, s[36:37]
	v_cndmask_b32_e64 v77, 0, v77, s[34:35]
	v_cndmask_b32_e64 v76, 0, v76, s[30:31]
	v_cndmask_b32_e64 v74, 0, v74, s[28:29]
	v_cndmask_b32_e64 v71, 0, v71, s[26:27]
	v_cndmask_b32_e64 v73, 0, v73, s[24:25]
	v_cndmask_b32_e64 v72, 0, v72, s[22:23]
	v_cndmask_b32_e64 v70, 0, v70, s[20:21]
	v_cndmask_b32_e64 v67, 0, v67, s[18:19]
	v_cndmask_b32_e64 v69, 0, v69, s[16:17]
	v_cndmask_b32_e64 v68, 0, v68, s[14:15]
	v_cndmask_b32_e64 v66, 0, v66, s[12:13]
	v_cndmask_b32_e64 v65, 0, v65, s[10:11]
	v_cndmask_b32_e64 v95, 0, v95, s[8:9]
	v_cndmask_b32_e64 v94, 0, v94, s[6:7]
	v_cndmask_b32_e64 v64, 0, v64, s[4:5]
	v_cndmask_b32_e32 v91, 0, v91, vcc

; #define LAS __attribute__((address_space(3)))
; #define ATT_SB() do {} while (0)
; #define ATT_SB() do {} while (0)
; #define ATT_SB() __builtin_amdgcn_sched_barrier(0)
; #define ATT_VLD(f) do { const int c_ = (f) >> 2, s_ = (f) & 3; const s16x4 lo_ = vtr(vbp + 4096 * s_ + vbase[0] + vcq[c_]); const s16x4 hh_ = vtr(vbp + 4096 * s_ + vbase[1] + vcq[c_]); \
;         vf[f] = (bf16x8){lo_[0], lo_[1], lo_[2], lo_[3], hh_[0], hh_[1], hh_[2], hh_[3]}; } while (0)
; #define ATT_PV(f) do { if (DO_PV) { o[(f) >> 2] = __builtin_amdgcn_mfma_f32_32x32x16_bf16(pa[(f) & 3], vf[f], o[(f) >> 2], 0, 0, 0); if ((f) + 4 < 16) ATT_VLD((f) + 4); } } while (0)
; #define ATT_EXP8(i) do { _Pragma("unroll") for (int r_ = 0; r_ < 8; ++r_) p[(i) >> 1][8 * ((i) & 1) + r_] = __builtin_amdgcn_exp2f(fminf(p[(i) >> 1][8 * ((i) & 1) + r_], 30.f)); } while (0)
; template <bool DO_PV> ...
;     f32x16 p[2];
; #pragma unroll
;     for (int r = 0; r < 16; ++r) { p[0][r] = 0.f; p[1][r] = 0.f; }
;     bf16x8 vf[16];
;     if (DO_PV) { ATT_VLD(0); ATT_VLD(1); ATT_VLD(2); ATT_VLD(3); }
;     {
;         bf16x8 ka[8], kc[8];
; #pragma unroll
;         for (int d0 = 0; d0 < 8; ++d0) { ka[d0] = *(const LAS bf16x8*)(kb + koff[d0]); kc[d0] = *(const LAS bf16x8*)(kb + 8192 + koff[d0]); }
;         ATT_SB();
; #pragma unroll
;         for (int d0 = 0; d0 < 8; ++d0) {
;             p[0] = __builtin_amdgcn_mfma_f32_32x32x16_bf16(ka[d0], qf[d0], p[0], 0, 0, 0);
;             p[1] = __builtin_amdgcn_mfma_f32_32x32x16_bf16(kc[d0], qf[d0], p[1], 0, 0, 0);
;         }
;     }
;     ATT_SB();
;     const bool need_mask = (k0 + 63 >= qw0);
;     float L[8], T[8];
;     ATT_PV(0); ATT_EXP8(0); ATT_SB();
;     ATT_PV(1); ATT_EXP8(1); ATT_SB();
;     ATT_PV(2); ATT_EXP8(2); ATT_SB();
;     ATT_PV(3); ATT_EXP8(3); ATT_SB();
.LBB0_620:
	s_and_b64 vcc, exec, s[4:5]
	s_cbranch_vccz .LBB0_624
	ds_read_b128 v[64:67], v168
	ds_read_b128 v[68:71], v168 offset:8192
	ds_read_b128 v[168:171], v167
	ds_read_b128 v[172:175], v167 offset:8192
	s_lshl_b32 s4, s72, 14
	s_add_i32 s4, s4, 0
	s_waitcnt lgkmcnt(0)
	v_mfma_f32_32x32x16_bf16 v[80:95], v[64:67], v[96:99], 0
	v_add_u32_e32 v159, s4, v188
	v_add_u32_e32 v194, s4, v189
	v_add_u32_e32 v176, v194, v191
	s_cmp_lt_i32 s66, s63
	v_mfma_f32_32x32x16_bf16 v[80:95], v[168:171], v[100:103], v[80:95]
	ds_read_b128 v[168:171], v166
	ds_read_b128 v[196:199], v166 offset:8192
	s_waitcnt lgkmcnt(0)
	v_mfma_f32_32x32x16_bf16 v[80:95], v[168:171], v[104:107], v[80:95]
	ds_read_b128 v[166:169], v165
	ds_read_b128 v[200:203], v165 offset:8192
	v_mfma_f32_32x32x16_bf16 v[64:79], v[68:71], v[96:99], 0
	s_waitcnt lgkmcnt(0)
	v_mfma_f32_32x32x16_bf16 v[80:95], v[166:169], v[108:111], v[80:95]
	ds_read_b128 v[166:169], v164
	ds_read_b128 v[204:207], v164 offset:8192
	ds_read_b128 v[208:211], v163
	v_mfma_f32_32x32x16_bf16 v[64:79], v[172:175], v[100:103], v[64:79]
	s_waitcnt lgkmcnt(0)
	v_mfma_f32_32x32x16_bf16 v[80:95], v[166:169], v[112:115], v[80:95]
	ds_read_b128 v[212:215], v163 offset:8192
	ds_read_b128 v[164:167], v162
	v_add_u32_e32 v168, v159, v190
	v_add_u32_e32 v169, v194, v190
	v_mfma_f32_32x32x16_bf16 v[64:79], v[196:199], v[104:107], v[64:79]
	v_mfma_f32_32x32x16_bf16 v[80:95], v[208:211], v[116:119], v[80:95]
	ds_read_b128 v[208:211], v162 offset:8192
	ds_read_b128 v[160:163], v149
	ds_read_b64_tr_b16 v[216:217], v168 offset:32768
	ds_read_b64_tr_b16 v[220:221], v168 offset:36864
	ds_read_b64_tr_b16 v[224:225], v168 offset:40960
	ds_read_b64_tr_b16 v[228:229], v168 offset:45056
	ds_read_b128 v[232:235], v149 offset:8192
	ds_read_b64_tr_b16 v[218:219], v169 offset:34816
	ds_read_b64_tr_b16 v[222:223], v169 offset:38912
	ds_read_b64_tr_b16 v[226:227], v169 offset:43008
	ds_read_b64_tr_b16 v[230:231], v169 offset:47104
	v_add_u32_e32 v149, v159, v191
	v_mfma_f32_32x32x16_bf16 v[64:79], v[200:203], v[108:111], v[64:79]
	s_waitcnt lgkmcnt(0)
	v_mfma_f32_32x32x16_bf16 v[80:95], v[164:167], v[120:123], v[80:95]
	v_mfma_f32_32x32x16_bf16 v[64:79], v[204:207], v[112:115], v[64:79]
	v_mfma_f32_32x32x16_bf16 v[80:95], v[160:163], v[124:127], v[80:95]
	v_mfma_f32_32x32x16_bf16 v[64:79], v[212:215], v[116:119], v[64:79]
	s_nop 10
	v_min_f32_e32 v80, 0x41f00000, v80
	v_exp_f32_e32 v160, v80
	v_min_f32_e32 v80, 0x41f00000, v82
	v_exp_f32_e32 v163, v80
	v_min_f32_e32 v80, 0x41f00000, v83
	v_exp_f32_e32 v161, v80
	v_min_f32_e32 v80, 0x41f00000, v84
	v_exp_f32_e32 v164, v80
	v_mfma_f32_32x32x16_bf16 v[64:79], v[208:211], v[120:123], v[64:79]
	v_min_f32_e32 v80, 0x41f00000, v85
	v_exp_f32_e32 v166, v80
	v_min_f32_e32 v80, 0x41f00000, v86
	v_exp_f32_e32 v167, v80
	v_min_f32_e32 v80, 0x41f00000, v87
	v_exp_f32_e32 v165, v80
	v_min_f32_e32 v80, 0x41f00000, v88
	v_exp_f32_e32 v88, v80
	v_mfma_f32_32x32x16_bf16 v[64:79], v[232:235], v[124:127], v[64:79]
	v_min_f32_e32 v80, 0x41f00000, v89
	v_exp_f32_e32 v168, v80
	v_min_f32_e32 v80, 0x41f00000, v90
	v_exp_f32_e32 v169, v80
	v_min_f32_e32 v80, 0x41f00000, v91
	v_mfma_f32_32x32x16_bf16 v[32:47], v[140:143], v[216:219], v[32:47]
	v_exp_f32_e32 v89, v80
	v_min_f32_e32 v80, 0x41f00000, v92
	v_exp_f32_e32 v90, v80
	v_min_f32_e32 v80, 0x41f00000, v93
	s_nop 1
	v_min_f32_e32 v64, 0x41f00000, v64
	v_exp_f32_e32 v92, v80
	v_min_f32_e32 v80, 0x41f00000, v94
	v_exp_f32_e32 v94, v64
	v_min_f32_e32 v64, 0x41f00000, v65
	v_exp_f32_e32 v170, v64
	v_mfma_f32_32x32x16_bf16 v[32:47], v[136:139], v[220:223], v[32:47]
	v_min_f32_e32 v64, 0x41f00000, v66
	v_exp_f32_e32 v171, v64
	v_min_f32_e32 v64, 0x41f00000, v67
	v_exp_f32_e32 v93, v80
	v_min_f32_e32 v80, 0x41f00000, v95
	v_exp_f32_e32 v95, v64
	v_min_f32_e32 v64, 0x41f00000, v68
	v_exp_f32_e32 v172, v64
	v_min_f32_e32 v64, 0x41f00000, v69
	v_exp_f32_e32 v174, v64
	v_mfma_f32_32x32x16_bf16 v[32:47], v[132:135], v[224:227], v[32:47]
	v_min_f32_e32 v64, 0x41f00000, v70
	v_exp_f32_e32 v175, v64
	v_min_f32_e32 v81, 0x41f00000, v81
	v_min_f32_e32 v64, 0x41f00000, v71
	v_min_f32_e32 v73, 0x41f00000, v73
	v_exp_f32_e32 v162, v81
	v_exp_f32_e32 v91, v80
	v_exp_f32_e32 v173, v64
	ds_read_b64_tr_b16 v[84:85], v149 offset:32768
	ds_read_b64_tr_b16 v[80:81], v149 offset:36864
	ds_read_b64_tr_b16 v[68:69], v149 offset:40960
	ds_read_b64_tr_b16 v[64:65], v149 offset:45056
	ds_read_b64_tr_b16 v[86:87], v176 offset:34816
	ds_read_b64_tr_b16 v[82:83], v176 offset:38912
	ds_read_b64_tr_b16 v[70:71], v176 offset:43008
	ds_read_b64_tr_b16 v[66:67], v176 offset:47104
	v_exp_f32_e32 v176, v73
	v_min_f32_e32 v73, 0x41f00000, v74
	v_exp_f32_e32 v177, v73
	v_min_f32_e32 v73, 0x41f00000, v75
	v_min_f32_e32 v75, 0x41f00000, v77
	v_min_f32_e32 v74, 0x41f00000, v76
	v_exp_f32_e32 v76, v75
	v_mfma_f32_32x32x16_bf16 v[32:47], v[128:131], v[228:231], v[32:47]
	v_min_f32_e32 v75, 0x41f00000, v78
	v_exp_f32_e32 v77, v75
	v_min_f32_e32 v72, 0x41f00000, v72
	v_min_f32_e32 v75, 0x41f00000, v79
	v_exp_f32_e32 v72, v72
	v_exp_f32_e32 v73, v73
	v_exp_f32_e32 v74, v74
	v_exp_f32_e32 v75, v75
	s_cbranch_scc1 .LBB0_623
; __device__ __forceinline__ int crow(int r, int hi) { return (r & 3) + 8 * (r >> 2) + 4 * hi; }
; #define ATT_SB() do {} while (0)
; #define ATT_SB() do {} while (0)
; #define ATT_SB() __builtin_amdgcn_sched_barrier(0)
; #define ATT_PV(f) do { if (DO_PV) { o[(f) >> 2] = __builtin_amdgcn_mfma_f32_32x32x16_bf16(pa[(f) & 3], vf[f], o[(f) >> 2], 0, 0, 0); if ((f) + 4 < 16) ATT_VLD((f) + 4); } } while (0)
; #define ATT_LBLK(j) do { const int ph_ = 1 - ((j) >> 2), g_ = 3 - ((j) & 3); \
;         const float w0_ = 1.0f + p[ph_][4 * g_], w1_ = 1.0f + p[ph_][4 * g_ + 1], w2_ = 1.0f + p[ph_][4 * g_ + 2], w3_ = 1.0f + p[ph_][4 * g_ + 3]; \
;         L[j] = __builtin_amdgcn_logf((w0_ * w1_) * (w2_ * w3_)); } while (0)
; template <bool DO_PV> ...
;     ...
;     if (need_mask) {
; #pragma unroll
;         for (int ph = 0; ph < 2; ++ph)
; #pragma unroll
;             for (int r = 0; r < 16; ++r) { const int key = k0 + 32 * ph + crow(r, hi); if (key >= qabs) p[ph][r] = 0.f; }
;     }
;     ATT_SB();
;     ATT_PV(4); ATT_LBLK(0); ATT_LBLK(1); ATT_SB();
;     ATT_PV(5); ATT_LBLK(2); ATT_LBLK(3); ATT_SB();
;     ATT_PV(6); ATT_LBLK(4); ATT_LBLK(5); ATT_SB();
;     ATT_PV(7); ATT_LBLK(6); ATT_LBLK(7); ATT_SB();
	v_add_u32_e32 v78, s66, v187
	v_subrev_u32_e32 v79, 63, v78
	v_cmp_lt_i32_e32 vcc, v79, v144
	v_subrev_u32_e32 v79, 62, v78
	v_cmp_lt_i32_e64 s[4:5], v79, v144
	s_or_b64 vcc, s[4:5], vcc
	v_subrev_u32_e32 v79, 61, v78
	v_cndmask_b32_e32 v160, 0, v160, vcc
	v_cmp_lt_i32_e32 vcc, v79, v144
	v_subrev_u32_e32 v79, 60, v78
	v_cndmask_b32_e64 v162, 0, v162, s[4:5]
	v_cndmask_b32_e32 v163, 0, v163, vcc
	v_cmp_lt_i32_e32 vcc, v79, v144
	v_subrev_u32_e32 v79, 55, v78
	s_nop 0
	v_cndmask_b32_e32 v161, 0, v161, vcc
	v_cmp_lt_i32_e32 vcc, v79, v144
	v_subrev_u32_e32 v79, 54, v78
	s_nop 0
	v_cndmask_b32_e32 v164, 0, v164, vcc
	v_cmp_lt_i32_e32 vcc, v79, v144
	v_subrev_u32_e32 v79, 53, v78
	s_nop 0
	v_cndmask_b32_e32 v166, 0, v166, vcc
	v_cmp_lt_i32_e32 vcc, v79, v144
	v_subrev_u32_e32 v79, 52, v78
	s_nop 0
	v_cndmask_b32_e32 v167, 0, v167, vcc
	v_cmp_lt_i32_e32 vcc, v79, v144
	v_subrev_u32_e32 v79, 47, v78
	s_nop 0
	v_cndmask_b32_e32 v165, 0, v165, vcc
	v_cmp_lt_i32_e32 vcc, v79, v144
	v_subrev_u32_e32 v79, 46, v78
	s_nop 0
	v_cndmask_b32_e32 v88, 0, v88, vcc
	v_cmp_lt_i32_e32 vcc, v79, v144
	v_subrev_u32_e32 v79, 45, v78
	s_nop 0
	v_cndmask_b32_e32 v168, 0, v168, vcc
	v_cmp_lt_i32_e32 vcc, v79, v144
	v_subrev_u32_e32 v79, 44, v78
	s_nop 0
	v_cndmask_b32_e32 v169, 0, v169, vcc
	v_cmp_lt_i32_e32 vcc, v79, v144
	v_subrev_u32_e32 v79, 39, v78
	s_nop 0
	v_cndmask_b32_e32 v89, 0, v89, vcc
	v_cmp_lt_i32_e32 vcc, v79, v144
	v_subrev_u32_e32 v79, 38, v78
	s_nop 0
	v_cndmask_b32_e32 v90, 0, v90, vcc
	v_cmp_lt_i32_e32 vcc, v79, v144
	v_subrev_u32_e32 v79, 37, v78
	s_nop 0
	v_cndmask_b32_e32 v92, 0, v92, vcc
	v_cmp_lt_i32_e32 vcc, v79, v144
	v_subrev_u32_e32 v79, 36, v78
	s_nop 0
	v_cndmask_b32_e32 v93, 0, v93, vcc
	v_cmp_lt_i32_e32 vcc, v79, v144
	v_subrev_u32_e32 v79, 31, v78
	v_cmp_lt_i32_e64 s[4:5], v79, v144
	v_subrev_u32_e32 v79, 30, v78
	v_cmp_lt_i32_e64 s[6:7], v79, v144
	v_subrev_u32_e32 v79, 29, v78
	v_cmp_lt_i32_e64 s[8:9], v79, v144
	v_subrev_u32_e32 v79, 28, v78
	v_cmp_lt_i32_e64 s[10:11], v79, v144
	v_subrev_u32_e32 v79, 23, v78
	v_cmp_lt_i32_e64 s[12:13], v79, v144
	v_subrev_u32_e32 v79, 22, v78
	v_cmp_lt_i32_e64 s[14:15], v79, v144
	v_subrev_u32_e32 v79, 21, v78
	v_cmp_lt_i32_e64 s[16:17], v79, v144
	v_subrev_u32_e32 v79, 20, v78
	v_cmp_lt_i32_e64 s[18:19], v79, v144
	v_add_u32_e32 v79, -15, v78
	v_cmp_lt_i32_e64 s[20:21], v79, v144
	v_add_u32_e32 v79, -14, v78
	v_cmp_lt_i32_e64 s[22:23], v79, v144
	v_add_u32_e32 v79, -13, v78
	v_cmp_lt_i32_e64 s[24:25], v79, v144
	v_add_u32_e32 v79, -12, v78
	v_cmp_lt_i32_e64 s[26:27], v79, v144
	v_add_u32_e32 v79, -7, v78
	v_cmp_lt_i32_e64 s[28:29], v79, v144
	v_add_u32_e32 v79, -6, v78
	v_cmp_lt_i32_e64 s[30:31], v79, v144
	v_add_u32_e32 v79, -5, v78
	v_add_u32_e32 v78, -4, v78
	v_cmp_lt_i32_e64 s[34:35], v79, v144
	v_cmp_lt_i32_e64 s[36:37], v78, v144
	s_or_b64 s[34:35], s[36:37], s[34:35]
	s_or_b64 s[30:31], s[34:35], s[30:31]
	s_or_b64 s[28:29], s[30:31], s[28:29]
	s_or_b64 s[26:27], s[28:29], s[26:27]
	s_or_b64 s[24:25], s[26:27], s[24:25]
	s_or_b64 s[22:23], s[24:25], s[22:23]
	s_or_b64 s[20:21], s[22:23], s[20:21]
	s_or_b64 s[18:19], s[20:21], s[18:19]
	s_or_b64 s[16:17], s[18:19], s[16:17]
	s_or_b64 s[14:15], s[16:17], s[14:15]
	s_or_b64 s[12:13], s[14:15], s[12:13]
	s_or_b64 s[10:11], s[12:13], s[10:11]
	s_or_b64 s[8:9], s[10:11], s[8:9]
	s_or_b64 s[6:7], s[8:9], s[6:7]
	s_or_b64 s[4:5], s[6:7], s[4:5]
	s_or_b64 vcc, s[4:5], vcc
	v_cndmask_b32_e64 v75, 0, v75, s[36:37]
	v_cndmask_b32_e64 v77, 0, v77, s[34:35]
	v_cndmask_b32_e64 v76, 0, v76, s[30:31]
	v_cndmask_b32_e64 v74, 0, v74, s[28:29]
	v_cndmask_b32_e64 v73, 0, v73, s[26:27]
	v_cndmask_b32_e64 v177, 0, v177, s[24:25]
	v_cndmask_b32_e64 v176, 0, v176, s[22:23]
	v_cndmask_b32_e64 v72, 0, v72, s[20:21]
	v_cndmask_b32_e64 v173, 0, v173, s[18:19]
	v_cndmask_b32_e64 v175, 0, v175, s[16:17]
	v_cndmask_b32_e64 v174, 0, v174, s[14:15]
	v_cndmask_b32_e64 v172, 0, v172, s[12:13]
	v_cndmask_b32_e64 v95, 0, v95, s[10:11]
	v_cndmask_b32_e64 v171, 0, v171, s[8:9]
	v_cndmask_b32_e64 v170, 0, v170, s[6:7]
	v_cndmask_b32_e64 v94, 0, v94, s[4:5]
	v_cndmask_b32_e32 v91, 0, v91, vcc
.LBB0_623:
	s_waitcnt lgkmcnt(0)
	v_mfma_f32_32x32x16_bf16 v[48:63], v[140:143], v[84:87], v[48:63]
	v_add_f32_e64 v196, v76, 1.0
	v_add_f32_e64 v197, v77, 1.0
	v_add_f32_e64 v198, v74, 1.0
	v_add_f32_e64 v199, v75, 1.0
	v_add_f32_e64 v86, v176, 1.0
	v_add_f32_e64 v87, v177, 1.0
	v_mul_f32_e32 v78, v196, v198
	v_mul_f32_e32 v79, v197, v199
	v_add_f32_e32 v200, 1.0, v72
	v_add_f32_e32 v201, 1.0, v73
	v_mul_f32_e32 v78, v78, v79
	v_log_f32_e32 v199, v78
	v_mfma_f32_32x32x16_bf16 v[48:63], v[136:139], v[80:83], v[48:63]
	v_mul_f32_e64 v78, v86, v200
	v_mul_f32_e64 v79, v87, v201
	v_add_f32_e64 v202, v174, 1.0
	v_add_f32_e64 v203, v175, 1.0
	v_mul_f32_e32 v78, v78, v79
	v_add_f32_e32 v204, 1.0, v172
	v_add_f32_e32 v205, 1.0, v173
	v_add_f32_e32 v210, 1.0, v92
	v_add_f32_e32 v211, 1.0, v93
	v_add_f32_e32 v212, 1.0, v90
	v_add_f32_e32 v213, 1.0, v91
	v_log_f32_e32 v201, v78
	v_mfma_f32_32x32x16_bf16 v[48:63], v[132:135], v[68:71], v[48:63]
	v_mul_f32_e64 v78, v202, v204
	v_mul_f32_e64 v79, v203, v205
	v_mul_f32_e64 v68, v210, v212
	v_mul_f32_e64 v69, v211, v213
	v_mul_f32_e32 v78, v78, v79
	v_add_f32_e32 v206, 1.0, v170
	v_add_f32_e32 v207, 1.0, v171
	v_add_f32_e32 v208, 1.0, v94
	v_add_f32_e32 v209, 1.0, v95
	v_mul_f32_e32 v68, v68, v69
	v_add_f32_e32 v214, 1.0, v168
	v_add_f32_e32 v215, 1.0, v169
	v_add_f32_e32 v216, 1.0, v88
	v_add_f32_e32 v217, 1.0, v89
	v_log_f32_e32 v205, v78
	v_mul_f32_e32 v78, v206, v208
	v_mul_f32_e32 v79, v207, v209
	v_log_f32_e32 v213, v68
	v_mul_f32_e32 v68, v214, v216
	v_mul_f32_e32 v69, v215, v217
	v_add_u32_e32 v149, v159, v192
	v_mul_f32_e32 v78, v78, v79
	v_mul_f32_e32 v68, v68, v69
	v_add_u32_e32 v218, v194, v192
	v_log_f32_e32 v209, v78
	v_log_f32_e32 v217, v68
	v_mfma_f32_32x32x16_bf16 v[48:63], v[128:131], v[64:67], v[48:63]
	ds_read_b64_tr_b16 v[64:65], v149 offset:32768
	ds_read_b64_tr_b16 v[68:69], v149 offset:36864
	ds_read_b64_tr_b16 v[78:79], v149 offset:40960
	ds_read_b64_tr_b16 v[82:83], v149 offset:45056
	ds_read_b64_tr_b16 v[66:67], v218 offset:34816
	ds_read_b64_tr_b16 v[70:71], v218 offset:38912
	ds_read_b64_tr_b16 v[80:81], v218 offset:43008
	ds_read_b64_tr_b16 v[84:85], v218 offset:47104
	v_add_f32_e32 v218, 1.0, v166
	v_add_f32_e32 v219, 1.0, v167
	v_add_f32_e32 v220, 1.0, v164
	v_add_f32_e32 v221, 1.0, v165
	v_add_f32_e32 v224, 1.0, v160
	v_add_f32_e32 v225, 1.0, v161
	v_mul_f32_e32 v222, v218, v220
	v_mul_f32_e32 v223, v219, v221
	v_add_u32_e32 v194, v194, v193
	v_mul_f32_e32 v149, v222, v223
	s_waitcnt lgkmcnt(0)
; __device__ __forceinline__ unsigned pk_bf16(float lo, float hi) { return pg8::cvt_pk_bf16(lo, hi); }
; #define ATT_SB() do {} while (0)
; #define ATT_SB() do {} while (0)
; #define ATT_SB() __builtin_amdgcn_sched_barrier(0)
; #define ATT_PV(f) do { if (DO_PV) { o[(f) >> 2] = __builtin_amdgcn_mfma_f32_32x32x16_bf16(pa[(f) & 3], vf[f], o[(f) >> 2], 0, 0, 0); if ((f) + 4 < 16) ATT_VLD((f) + 4); } } while (0)
; #define ATT_XCH(j) do { const float own_ = L[j]; const auto rr_ = __builtin_amdgcn_permlane32_swap(__float_as_uint(own_), __float_as_uint(own_), false, false); \
;         const float a0_ = __uint_as_float(rr_[0]), a1_ = __uint_as_float(rr_[1]); const float oth_ = (a0_ == own_) ? a1_ : a0_; \
;         T[j] = run + (hi ? 0.f : oth_) + own_; run += a0_ + a1_; } while (0)
; #define ATT_WGT(j) do { const int ph_ = 1 - ((j) >> 2), g_ = 3 - ((j) & 3); float cf_ = __builtin_amdgcn_exp2f(-T[j]); \
;         _Pragma("unroll") for (int e_ = 0; e_ < 4; ++e_) { const float ev_ = p[ph_][4 * g_ + e_]; p[ph_][4 * g_ + e_] = ev_ * cf_; if (e_ < 3) cf_ *= (1.0f + ev_); } } while (0)
; template <bool DO_PV> ...
;     ...
;     float run = carry;
;     ATT_PV(8); ATT_XCH(0); ATT_XCH(1); ATT_SB();
;     ATT_PV(9); ATT_XCH(2); ATT_XCH(3); ATT_SB();
;     ATT_PV(10); ATT_XCH(4); ATT_XCH(5); ATT_SB();
;     ATT_PV(11); ATT_XCH(6); ATT_XCH(7); ATT_SB();
;     carry = run;
;     ATT_PV(12); ATT_WGT(0); ATT_WGT(1); ATT_SB();
;     ATT_PV(13); ATT_WGT(2); ATT_WGT(3); ATT_SB();
;     ATT_PV(14); ATT_WGT(4); ATT_WGT(5); ATT_SB();
;     ATT_PV(15); ATT_WGT(6); ATT_WGT(7); ATT_SB();
; #pragma unroll
;     for (int s = 0; s < 4; ++s) { const int ph = s >> 1, rb = 8 * (s & 1);
;         u32x4 w; w.x = pk_bf16(p[ph][rb], p[ph][rb + 1]); w.y = pk_bf16(p[ph][rb + 2], p[ph][rb + 3]); w.z = pk_bf16(p[ph][rb + 4], p[ph][rb + 5]); w.w = pk_bf16(p[ph][rb + 6], p[ph][rb + 7]);
;         pa[s] = __builtin_bit_cast(bf16x8, w); }
	v_mfma_f32_32x32x16_bf16 v[0:15], v[140:143], v[64:67], v[0:15]
	v_mov_b32_e32 v64, v199
	v_mov_b32_e32 v65, v199
	s_nop 1
	v_permlane32_swap_b32_e32 v64, v65
	v_add_f32_e64 v222, v162, 1.0
	v_add_f32_e64 v223, v163, 1.0
	v_cmp_eq_f32_e32 vcc, v199, v64
	v_mul_f32_e32 v226, v222, v224
	v_mul_f32_e32 v227, v223, v225
	v_add_u32_e32 v225, v159, v193
	v_cndmask_b32_e32 v66, v64, v65, vcc
	v_add_f32_e32 v64, v64, v65
	v_mov_b32_e32 v159, v201
	v_mov_b32_e32 v65, v201
	v_cndmask_b32_e64 v66, 0, v66, s[0:1]
	s_nop 0
	v_permlane32_swap_b32_e32 v159, v65
	v_add_f32_e32 v66, v158, v66
	v_cmp_eq_f32_e32 vcc, v201, v159
	v_add_f32_e32 v199, v199, v66
	v_mfma_f32_32x32x16_bf16 v[0:15], v[136:139], v[68:71], v[0:15]
	v_cndmask_b32_e32 v66, v159, v65, vcc
	v_cndmask_b32_e64 v66, 0, v66, s[0:1]
	v_add_f32_e64 v64, v158, v64
	v_add_f32_e64 v65, v159, v65
	v_exp_f32_e64 v199, -v199
	v_add_f32_e32 v228, v64, v66
	v_add_f32_e32 v64, v64, v65
	v_mov_b32_e32 v65, v64
	v_mov_b32_e32 v66, v205
	v_mov_b32_e32 v65, v205
	s_nop 1
	v_permlane32_swap_b32_e32 v65, v66
	v_cmp_eq_f32_e32 vcc, v205, v65
	v_mfma_f32_32x32x16_bf16 v[0:15], v[132:135], v[78:81], v[0:15]
	v_log_f32_e32 v149, v149
	v_cndmask_b32_e32 v67, v65, v66, vcc
	v_cndmask_b32_e64 v67, 0, v67, s[0:1]
	v_add_f32_e32 v229, v64, v67
	v_add_f32_e32 v66, v65, v66
	v_mov_b32_e32 v65, v209
	v_mov_b32_e32 v67, v209
	s_nop 1
	v_permlane32_swap_b32_e32 v65, v67
	v_cmp_eq_f32_e32 vcc, v209, v65
	v_mfma_f32_32x32x16_bf16 v[0:15], v[128:131], v[82:85], v[0:15]
	v_mul_f32_e32 v221, v226, v227
	v_cndmask_b32_e32 v68, v65, v67, vcc
	v_cndmask_b32_e64 v68, 0, v68, s[0:1]
	v_add_f32_e64 v64, v64, v66
	v_add_f32_e64 v65, v65, v67
	v_mov_b32_e32 v66, v213
	v_add_f32_e32 v230, v64, v68
	v_add_f32_e32 v64, v64, v65
	v_mov_b32_e32 v65, v64
	v_log_f32_e32 v221, v221
	v_mov_b32_e32 v65, v213
	s_nop 1
	v_permlane32_swap_b32_e32 v65, v66
	v_cmp_eq_f32_e32 vcc, v213, v65
	v_mov_b32_e32 v227, v221
	s_nop 0
	v_cndmask_b32_e32 v67, v65, v66, vcc
	v_cndmask_b32_e64 v67, 0, v67, s[0:1]
	v_add_f32_e32 v231, v64, v67
	v_add_f32_e32 v66, v65, v66
	v_mov_b32_e32 v65, v217
	v_mov_b32_e32 v67, v217
	s_nop 1
	v_permlane32_swap_b32_e32 v65, v67
	v_cmp_eq_f32_e32 vcc, v217, v65
	s_nop 1
	v_cndmask_b32_e32 v68, v65, v67, vcc
	v_cndmask_b32_e64 v68, 0, v68, s[0:1]
	v_add_f32_e32 v64, v64, v66
	v_add_f32_e32 v65, v65, v67
	s_nop 0
	v_add_f32_e32 v232, v64, v68
	v_add_f32_e32 v158, v64, v65
	v_add_f32_e32 v159, v65, v64
	ds_read_b64_tr_b16 v[64:65], v225 offset:32768
	ds_read_b64_tr_b16 v[68:69], v225 offset:36864
	ds_read_b64_tr_b16 v[78:79], v225 offset:40960
	ds_read_b64_tr_b16 v[82:83], v225 offset:45056
	ds_read_b64_tr_b16 v[66:67], v194 offset:34816
	ds_read_b64_tr_b16 v[70:71], v194 offset:38912
	ds_read_b64_tr_b16 v[80:81], v194 offset:43008
	ds_read_b64_tr_b16 v[84:85], v194 offset:47104
	s_waitcnt lgkmcnt(0)
	v_mfma_f32_32x32x16_bf16 v[16:31], v[140:143], v[64:67], v[16:31]
	v_mul_f32_e32 v64, v198, v199
	v_mul_f32_e32 v141, v76, v64
	v_mul_f32_e32 v64, v196, v64
	v_mul_f32_e32 v142, v77, v64
	v_mul_f32_e32 v64, v197, v64
	v_mul_f32_e32 v143, v75, v64
	v_add_f32_e32 v64, v201, v228
	v_exp_f32_e64 v64, -v64
	v_add_f32_e32 v65, v205, v229
	v_exp_f32_e64 v65, -v65
	v_mul_f32_e32 v140, v74, v199
	v_mul_f32_e32 v76, v72, v64
	v_mul_f32_e32 v64, v200, v64
	v_mul_f32_e32 v77, v176, v64
	v_mul_f32_e32 v64, v86, v64
	v_mul_f32_e32 v86, v177, v64
	v_mul_f32_e32 v64, v87, v64
	v_mul_f32_e32 v87, v73, v64
	v_add_f32_e32 v64, v209, v230
	v_mul_f32_e32 v74, v172, v65
	v_mul_f32_e32 v65, v204, v65
	v_mfma_f32_32x32x16_bf16 v[16:31], v[136:139], v[68:71], v[16:31]
	v_mul_f32_e32 v75, v174, v65
	v_mul_f32_e32 v65, v202, v65
	v_exp_f32_e64 v64, -v64
	v_mul_f32_e32 v136, v175, v65
	v_mul_f32_e32 v65, v203, v65
	v_mul_f32_e32 v137, v173, v65
	v_add_f32_e32 v65, v213, v231
	v_exp_f32_e64 v65, -v65
	v_mov_b32_e32 v159, v149
	v_mov_b32_e32 v194, v149
	v_mul_f32_e32 v72, v94, v64
	v_mul_f32_e32 v64, v208, v64
	v_permlane32_swap_b32_e32 v159, v194
	v_mul_f32_e32 v73, v170, v64
	v_mul_f32_e32 v64, v206, v64
	v_cmp_eq_f32_e32 vcc, v149, v159
	v_add_f32_e32 v66, v217, v232
	v_mul_f32_e32 v94, v171, v64
	v_mul_f32_e32 v64, v207, v64
	v_cndmask_b32_e32 v225, v159, v194, vcc
	v_mul_f32_e32 v95, v95, v64
	v_mul_f32_e32 v70, v90, v65
	v_mul_f32_e32 v64, v212, v65
	v_exp_f32_e64 v65, -v66
	v_cndmask_b32_e64 v225, 0, v225, s[0:1]
	v_mfma_f32_32x32x16_bf16 v[16:31], v[132:135], v[78:81], v[16:31]
	v_add_f32_e32 v225, v158, v225
	v_add_f32_e32 v226, v159, v194
	v_mov_b32_e32 v159, v221
	v_mul_f32_e32 v71, v92, v64
	v_mul_f32_e32 v64, v210, v64
	v_permlane32_swap_b32_e32 v159, v227
	v_add_f32_e32 v67, v149, v225
	v_mul_f32_e32 v78, v93, v64
	v_mul_f32_e32 v64, v211, v64
	v_cmp_eq_f32_e32 vcc, v221, v159
	v_mul_f32_e32 v79, v91, v64
	v_mul_f32_e32 v68, v88, v65
	v_mul_f32_e32 v64, v216, v65
	v_exp_f32_e64 v65, -v67
	v_cndmask_b32_e32 v194, v159, v227, vcc
	v_cndmask_b32_e64 v194, 0, v194, s[0:1]
	v_add_f32_e32 v158, v158, v226
	v_add_f32_e32 v159, v159, v227
	v_mul_f32_e32 v69, v168, v64
	v_mul_f32_e32 v64, v214, v64
	v_add_f32_e32 v194, v158, v194
	v_mul_f32_e32 v80, v169, v64
	v_mul_f32_e32 v64, v215, v64
	v_mul_f32_e32 v81, v89, v64
	v_mul_f32_e32 v66, v164, v65
	v_mul_f32_e32 v64, v220, v65
	v_add_f32_e32 v65, v221, v194
	v_mfma_f32_32x32x16_bf16 v[16:31], v[128:131], v[82:85], v[16:31]
	v_exp_f32_e64 v65, -v65
	v_mul_f32_e32 v67, v166, v64
	v_mul_f32_e32 v64, v218, v64
	v_mul_f32_e32 v82, v167, v64
	v_mul_f32_e32 v64, v219, v64
	v_mul_f32_e32 v83, v165, v64
	v_mul_f32_e32 v64, v160, v65
	v_mul_f32_e32 v65, v224, v65
	v_mul_f32_e32 v84, v162, v65
	v_mul_f32_e32 v65, v222, v65
	v_mul_f32_e32 v85, v163, v65
	v_mul_f32_e32 v65, v223, v65
	v_add_f32_e32 v159, v158, v159
	v_mul_f32_e32 v65, v161, v65
	v_cvt_pk_bf16_f32 v64, v64, v84
	v_cvt_pk_bf16_f32 v65, v85, v65
	v_cvt_pk_bf16_f32 v66, v66, v67
	v_cvt_pk_bf16_f32 v67, v82, v83
	v_cvt_pk_bf16_f32 v68, v68, v69
	v_cvt_pk_bf16_f32 v69, v80, v81
	v_cvt_pk_bf16_f32 v70, v70, v71
	v_cvt_pk_bf16_f32 v71, v78, v79
	v_cvt_pk_bf16_f32 v72, v72, v73
	v_cvt_pk_bf16_f32 v73, v94, v95
	v_cvt_pk_bf16_f32 v74, v74, v75
	v_cvt_pk_bf16_f32 v75, v136, v137
	v_cvt_pk_bf16_f32 v76, v76, v77
	v_cvt_pk_bf16_f32 v77, v86, v87
	v_cvt_pk_bf16_f32 v78, v140, v141
	v_cvt_pk_bf16_f32 v79, v142, v143
